# prep: modulation GEMV hand-written (all 18 silu inputs and 60 weight rows per lane in flight, LDS broadcast of silu values, cross-wave reduction) on top of range-based weight prep
# baseline (speedup 1.0000x reference)
.Lmd_entry:
	v_readlane_b32 s15, v253, 0
	s_mul_hi_u32 s12, s15, 0x5555556
	s_mul_i32 s16, s12, 48
	s_sub_u32 s13, s15, s16
	s_lshl_b32 s13, s13, 6
	v_readlane_b32 s2, v253, 3
	v_readlane_b32 s3, v253, 4
	v_readlane_b32 s4, v253, 7
	v_readlane_b32 s5, v253, 8
	v_readlane_b32 s6, v253, 11
	v_readlane_b32 s7, v253, 12
	v_readlane_b32 s8, v253, 13
	v_readlane_b32 s9, v253, 14
	v_readfirstlane_b32 s14, v143
	s_lshr_b32 s14, s14, 6
	v_lshlrev_b32_e32 v153, 2, v143
	global_load_dword v160, v153, s[2:3]
	s_add_u32 s2, s2, 0x800
	s_addc_u32 s3, s3, 0
	global_load_dword v161, v153, s[2:3]
	s_add_u32 s2, s2, 0x800
	s_addc_u32 s3, s3, 0
	global_load_dword v162, v153, s[2:3]
	s_add_u32 s2, s2, 0x800
	s_addc_u32 s3, s3, 0
	global_load_dword v163, v153, s[2:3]
	s_add_u32 s2, s2, 0x800
	s_addc_u32 s3, s3, 0
	global_load_dword v164, v153, s[2:3]
	s_add_u32 s2, s2, 0x800
	s_addc_u32 s3, s3, 0
	global_load_dword v165, v153, s[2:3]
	s_add_u32 s2, s2, 0x800
	s_addc_u32 s3, s3, 0
	global_load_dword v166, v153, s[2:3]
	s_add_u32 s2, s2, 0x800
	s_addc_u32 s3, s3, 0
	global_load_dword v167, v153, s[2:3]
	s_add_u32 s2, s2, 0x800
	s_addc_u32 s3, s3, 0
	global_load_dword v168, v153, s[2:3]
	s_add_u32 s2, s2, 0x800
	s_addc_u32 s3, s3, 0
	global_load_dword v169, v153, s[2:3]
	s_add_u32 s2, s2, 0x800
	s_addc_u32 s3, s3, 0
	global_load_dword v170, v153, s[2:3]
	s_add_u32 s2, s2, 0x800
	s_addc_u32 s3, s3, 0
	global_load_dword v171, v153, s[2:3]
	s_add_u32 s2, s2, 0x800
	s_addc_u32 s3, s3, 0
	global_load_dword v172, v153, s[2:3]
	s_add_u32 s2, s2, 0x800
	s_addc_u32 s3, s3, 0
	global_load_dword v173, v153, s[2:3]
	s_add_u32 s2, s2, 0x800
	s_addc_u32 s3, s3, 0
	global_load_dword v174, v153, s[2:3]
	s_add_u32 s2, s2, 0x800
	s_addc_u32 s3, s3, 0
	global_load_dword v175, v153, s[2:3]
	s_add_u32 s2, s2, 0x800
	s_addc_u32 s3, s3, 0
	global_load_dword v176, v153, s[4:5]
	global_load_dword v177, v153, s[4:5] offset:2048
	s_lshl_b32 s15, s12, 10
	s_lshl_b32 s16, s14, 7
	s_add_u32 s15, s15, s16
	s_mul_i32 s15, s15, 12288
	s_lshl_b32 s16, s13, 2
	s_add_u32 s15, s15, s16
	s_add_u32 s10, s6, s15
	s_addc_u32 s11, s7, 0
	v_and_b32_e32 v154, 63, v143
	v_lshlrev_b32_e32 v154, 2, v154
	global_load_dword v60, v154, s[10:11]
	s_add_u32 s10, s10, 0x3000
	s_addc_u32 s11, s11, 0
	global_load_dword v61, v154, s[10:11]
	s_add_u32 s10, s10, 0x3000
	s_addc_u32 s11, s11, 0
	global_load_dword v62, v154, s[10:11]
	s_add_u32 s10, s10, 0x3000
	s_addc_u32 s11, s11, 0
	global_load_dword v63, v154, s[10:11]
	s_add_u32 s10, s10, 0x3000
	s_addc_u32 s11, s11, 0
	global_load_dword v64, v154, s[10:11]
	s_add_u32 s10, s10, 0x3000
	s_addc_u32 s11, s11, 0
	global_load_dword v65, v154, s[10:11]
	s_add_u32 s10, s10, 0x3000
	s_addc_u32 s11, s11, 0
	global_load_dword v66, v154, s[10:11]
	s_add_u32 s10, s10, 0x3000
	s_addc_u32 s11, s11, 0
	global_load_dword v67, v154, s[10:11]
	s_add_u32 s10, s10, 0x3000
	s_addc_u32 s11, s11, 0
	global_load_dword v68, v154, s[10:11]
	s_add_u32 s10, s10, 0x3000
	s_addc_u32 s11, s11, 0
	global_load_dword v69, v154, s[10:11]
	s_add_u32 s10, s10, 0x3000
	s_addc_u32 s11, s11, 0
	global_load_dword v70, v154, s[10:11]
	s_add_u32 s10, s10, 0x3000
	s_addc_u32 s11, s11, 0
	global_load_dword v71, v154, s[10:11]
	s_add_u32 s10, s10, 0x3000
	s_addc_u32 s11, s11, 0
	global_load_dword v72, v154, s[10:11]
	s_add_u32 s10, s10, 0x3000
	s_addc_u32 s11, s11, 0
	global_load_dword v73, v154, s[10:11]
	s_add_u32 s10, s10, 0x3000
	s_addc_u32 s11, s11, 0
	global_load_dword v74, v154, s[10:11]
	s_add_u32 s10, s10, 0x3000
	s_addc_u32 s11, s11, 0
	global_load_dword v75, v154, s[10:11]
	s_add_u32 s10, s10, 0x3000
	s_addc_u32 s11, s11, 0
	global_load_dword v76, v154, s[10:11]
	s_add_u32 s10, s10, 0x3000
	s_addc_u32 s11, s11, 0
	global_load_dword v77, v154, s[10:11]
	s_add_u32 s10, s10, 0x3000
	s_addc_u32 s11, s11, 0
	global_load_dword v78, v154, s[10:11]
	s_add_u32 s10, s10, 0x3000
	s_addc_u32 s11, s11, 0
	global_load_dword v79, v154, s[10:11]
	s_add_u32 s10, s10, 0x3000
	s_addc_u32 s11, s11, 0
	global_load_dword v80, v154, s[10:11]
	s_add_u32 s10, s10, 0x3000
	s_addc_u32 s11, s11, 0
	global_load_dword v81, v154, s[10:11]
	s_add_u32 s10, s10, 0x3000
	s_addc_u32 s11, s11, 0
	global_load_dword v83, v154, s[10:11]
	s_add_u32 s10, s10, 0x3000
	s_addc_u32 s11, s11, 0
	global_load_dword v84, v154, s[10:11]
	s_add_u32 s10, s10, 0x3000
	s_addc_u32 s11, s11, 0
	global_load_dword v85, v154, s[10:11]
	s_add_u32 s10, s10, 0x3000
	s_addc_u32 s11, s11, 0
	global_load_dword v86, v154, s[10:11]
	s_add_u32 s10, s10, 0x3000
	s_addc_u32 s11, s11, 0
	global_load_dword v87, v154, s[10:11]
	s_add_u32 s10, s10, 0x3000
	s_addc_u32 s11, s11, 0
	global_load_dword v88, v154, s[10:11]
	s_add_u32 s10, s10, 0x3000
	s_addc_u32 s11, s11, 0
	global_load_dword v89, v154, s[10:11]
	s_add_u32 s10, s10, 0x3000
	s_addc_u32 s11, s11, 0
	global_load_dword v90, v154, s[10:11]
	s_add_u32 s10, s10, 0x3000
	s_addc_u32 s11, s11, 0
	global_load_dword v91, v154, s[10:11]
	s_add_u32 s10, s10, 0x3000
	s_addc_u32 s11, s11, 0
	global_load_dword v92, v154, s[10:11]
	s_add_u32 s10, s10, 0x3000
	s_addc_u32 s11, s11, 0
	global_load_dword v93, v154, s[10:11]
	s_add_u32 s10, s10, 0x3000
	s_addc_u32 s11, s11, 0
	global_load_dword v94, v154, s[10:11]
	s_add_u32 s10, s10, 0x3000
	s_addc_u32 s11, s11, 0
	global_load_dword v95, v154, s[10:11]
	s_add_u32 s10, s10, 0x3000
	s_addc_u32 s11, s11, 0
	global_load_dword v96, v154, s[10:11]
	s_add_u32 s10, s10, 0x3000
	s_addc_u32 s11, s11, 0
	global_load_dword v97, v154, s[10:11]
	s_add_u32 s10, s10, 0x3000
	s_addc_u32 s11, s11, 0
	global_load_dword v98, v154, s[10:11]
	s_add_u32 s10, s10, 0x3000
	s_addc_u32 s11, s11, 0
	global_load_dword v99, v154, s[10:11]
	s_add_u32 s10, s10, 0x3000
	s_addc_u32 s11, s11, 0
	global_load_dword v100, v154, s[10:11]
	s_add_u32 s10, s10, 0x3000
	s_addc_u32 s11, s11, 0
	global_load_dword v101, v154, s[10:11]
	s_add_u32 s10, s10, 0x3000
	s_addc_u32 s11, s11, 0
	global_load_dword v102, v154, s[10:11]
	s_add_u32 s10, s10, 0x3000
	s_addc_u32 s11, s11, 0
	global_load_dword v103, v154, s[10:11]
	s_add_u32 s10, s10, 0x3000
	s_addc_u32 s11, s11, 0
	global_load_dword v104, v154, s[10:11]
	s_add_u32 s10, s10, 0x3000
	s_addc_u32 s11, s11, 0
	s_mov_b32 s17, 0xbfb8aa3b
	s_waitcnt vmcnt(61)
	v_mul_f32_e32 v155, s17, v160
	v_exp_f32_e32 v155, v155
	s_nop 0
	v_add_f32_e32 v155, 1.0, v155
	v_rcp_f32_e32 v155, v155
	s_nop 0
	v_mul_f32_e32 v155, v160, v155
	ds_write_b32 v153, v155 offset:0
	s_waitcnt vmcnt(60)
	v_mul_f32_e32 v156, s17, v161
	v_exp_f32_e32 v156, v156
	s_nop 0
	v_add_f32_e32 v156, 1.0, v156
	v_rcp_f32_e32 v156, v156
	s_nop 0
	v_mul_f32_e32 v156, v161, v156
	ds_write_b32 v153, v156 offset:2048
	s_waitcnt vmcnt(59)
	v_mul_f32_e32 v157, s17, v162
	v_exp_f32_e32 v157, v157
	s_nop 0
	v_add_f32_e32 v157, 1.0, v157
	v_rcp_f32_e32 v157, v157
	s_nop 0
	v_mul_f32_e32 v157, v162, v157
	ds_write_b32 v153, v157 offset:4096
	s_waitcnt vmcnt(58)
	v_mul_f32_e32 v155, s17, v163
	v_exp_f32_e32 v155, v155
	s_nop 0
	v_add_f32_e32 v155, 1.0, v155
	v_rcp_f32_e32 v155, v155
	s_nop 0
	v_mul_f32_e32 v155, v163, v155
	ds_write_b32 v153, v155 offset:6144
	s_waitcnt vmcnt(57)
	v_mul_f32_e32 v156, s17, v164
	v_exp_f32_e32 v156, v156
	s_nop 0
	v_add_f32_e32 v156, 1.0, v156
	v_rcp_f32_e32 v156, v156
	s_nop 0
	v_mul_f32_e32 v156, v164, v156
	ds_write_b32 v153, v156 offset:8192
	s_waitcnt vmcnt(56)
	v_mul_f32_e32 v157, s17, v165
	v_exp_f32_e32 v157, v157
	s_nop 0
	v_add_f32_e32 v157, 1.0, v157
	v_rcp_f32_e32 v157, v157
	s_nop 0
	v_mul_f32_e32 v157, v165, v157
	ds_write_b32 v153, v157 offset:10240
	s_waitcnt vmcnt(55)
	v_mul_f32_e32 v155, s17, v166
	v_exp_f32_e32 v155, v155
	s_nop 0
	v_add_f32_e32 v155, 1.0, v155
	v_rcp_f32_e32 v155, v155
	s_nop 0
	v_mul_f32_e32 v155, v166, v155
	ds_write_b32 v153, v155 offset:12288
	s_waitcnt vmcnt(54)
	v_mul_f32_e32 v156, s17, v167
	v_exp_f32_e32 v156, v156
	s_nop 0
	v_add_f32_e32 v156, 1.0, v156
	v_rcp_f32_e32 v156, v156
	s_nop 0
	v_mul_f32_e32 v156, v167, v156
	ds_write_b32 v153, v156 offset:14336
	s_waitcnt vmcnt(53)
	v_mul_f32_e32 v157, s17, v168
	v_exp_f32_e32 v157, v157
	s_nop 0
	v_add_f32_e32 v157, 1.0, v157
	v_rcp_f32_e32 v157, v157
	s_nop 0
	v_mul_f32_e32 v157, v168, v157
	ds_write_b32 v153, v157 offset:16384
	s_waitcnt vmcnt(52)
	v_mul_f32_e32 v155, s17, v169
	v_exp_f32_e32 v155, v155
	s_nop 0
	v_add_f32_e32 v155, 1.0, v155
	v_rcp_f32_e32 v155, v155
	s_nop 0
	v_mul_f32_e32 v155, v169, v155
	ds_write_b32 v153, v155 offset:18432
	s_waitcnt vmcnt(51)
	v_mul_f32_e32 v156, s17, v170
	v_exp_f32_e32 v156, v156
	s_nop 0
	v_add_f32_e32 v156, 1.0, v156
	v_rcp_f32_e32 v156, v156
	s_nop 0
	v_mul_f32_e32 v156, v170, v156
	ds_write_b32 v153, v156 offset:20480
	s_waitcnt vmcnt(50)
	v_mul_f32_e32 v157, s17, v171
	v_exp_f32_e32 v157, v157
	s_nop 0
	v_add_f32_e32 v157, 1.0, v157
	v_rcp_f32_e32 v157, v157
	s_nop 0
	v_mul_f32_e32 v157, v171, v157
	ds_write_b32 v153, v157 offset:22528
	s_waitcnt vmcnt(49)
	v_mul_f32_e32 v155, s17, v172
	v_exp_f32_e32 v155, v155
	s_nop 0
	v_add_f32_e32 v155, 1.0, v155
	v_rcp_f32_e32 v155, v155
	s_nop 0
	v_mul_f32_e32 v155, v172, v155
	ds_write_b32 v153, v155 offset:24576
	s_waitcnt vmcnt(48)
	v_mul_f32_e32 v156, s17, v173
	v_exp_f32_e32 v156, v156
	s_nop 0
	v_add_f32_e32 v156, 1.0, v156
	v_rcp_f32_e32 v156, v156
	s_nop 0
	v_mul_f32_e32 v156, v173, v156
	ds_write_b32 v153, v156 offset:26624
	s_waitcnt vmcnt(47)
	v_mul_f32_e32 v157, s17, v174
	v_exp_f32_e32 v157, v157
	s_nop 0
	v_add_f32_e32 v157, 1.0, v157
	v_rcp_f32_e32 v157, v157
	s_nop 0
	v_mul_f32_e32 v157, v174, v157
	ds_write_b32 v153, v157 offset:28672
	s_waitcnt vmcnt(46)
	v_mul_f32_e32 v155, s17, v175
	v_exp_f32_e32 v155, v155
	s_nop 0
	v_add_f32_e32 v155, 1.0, v155
	v_rcp_f32_e32 v155, v155
	s_nop 0
	v_mul_f32_e32 v155, v175, v155
	ds_write_b32 v153, v155 offset:30720
	s_waitcnt vmcnt(45)
	v_mul_f32_e32 v156, s17, v176
	v_exp_f32_e32 v156, v156
	s_nop 0
	v_add_f32_e32 v156, 1.0, v156
	v_rcp_f32_e32 v156, v156
	s_nop 0
	v_mul_f32_e32 v156, v176, v156
	ds_write_b32 v153, v156 offset:32768
	s_waitcnt vmcnt(44)
	v_mul_f32_e32 v157, s17, v177
	v_exp_f32_e32 v157, v157
	s_nop 0
	v_add_f32_e32 v157, 1.0, v157
	v_rcp_f32_e32 v157, v157
	s_nop 0
	v_mul_f32_e32 v157, v177, v157
	ds_write_b32 v153, v157 offset:34816
	global_load_dword v105, v154, s[10:11]
	s_add_u32 s10, s10, 0x3000
	s_addc_u32 s11, s11, 0
	global_load_dword v106, v154, s[10:11]
	s_add_u32 s10, s10, 0x3000
	s_addc_u32 s11, s11, 0
	global_load_dword v107, v154, s[10:11]
	s_add_u32 s10, s10, 0x3000
	s_addc_u32 s11, s11, 0
	global_load_dword v108, v154, s[10:11]
	s_add_u32 s10, s10, 0x3000
	s_addc_u32 s11, s11, 0
	global_load_dword v109, v154, s[10:11]
	s_add_u32 s10, s10, 0x3000
	s_addc_u32 s11, s11, 0
	global_load_dword v110, v154, s[10:11]
	s_add_u32 s10, s10, 0x3000
	s_addc_u32 s11, s11, 0
	global_load_dword v111, v154, s[10:11]
	s_add_u32 s10, s10, 0x3000
	s_addc_u32 s11, s11, 0
	global_load_dword v112, v154, s[10:11]
	s_add_u32 s10, s10, 0x3000
	s_addc_u32 s11, s11, 0
	global_load_dword v113, v154, s[10:11]
	s_add_u32 s10, s10, 0x3000
	s_addc_u32 s11, s11, 0
	global_load_dword v114, v154, s[10:11]
	s_add_u32 s10, s10, 0x3000
	s_addc_u32 s11, s11, 0
	global_load_dword v115, v154, s[10:11]
	s_add_u32 s10, s10, 0x3000
	s_addc_u32 s11, s11, 0
	global_load_dword v116, v154, s[10:11]
	s_add_u32 s10, s10, 0x3000
	s_addc_u32 s11, s11, 0
	global_load_dword v117, v154, s[10:11]
	s_add_u32 s10, s10, 0x3000
	s_addc_u32 s11, s11, 0
	global_load_dword v118, v154, s[10:11]
	s_add_u32 s10, s10, 0x3000
	s_addc_u32 s11, s11, 0
	global_load_dword v119, v154, s[10:11]
	s_add_u32 s10, s10, 0x3000
	s_addc_u32 s11, s11, 0
	global_load_dword v120, v154, s[10:11]
	s_add_u32 s10, s10, 0x3000
	s_addc_u32 s11, s11, 0
	v_mov_b32_e32 v144, 0
	v_mov_b32_e32 v145, 0
	v_mov_b32_e32 v146, 0
	v_mov_b32_e32 v147, 0
	v_mov_b32_e32 v148, 0
	v_mov_b32_e32 v149, 0
	v_mov_b32_e32 v150, 0
	v_mov_b32_e32 v151, 0
	v_mov_b32_e32 v152, 0
	s_waitcnt lgkmcnt(0)
	s_barrier
	s_lshl_b32 s15, s14, 9
	v_mov_b32_e32 v156, s15
	ds_read_b128 v[2:5], v156 offset:0
	ds_read_b128 v[6:9], v156 offset:4096
	ds_read_b128 v[10:13], v156 offset:8192
	ds_read_b128 v[14:17], v156 offset:12288
	ds_read_b128 v[18:21], v156 offset:16384
	ds_read_b128 v[22:25], v156 offset:20480
	ds_read_b128 v[26:29], v156 offset:24576
	ds_read_b128 v[30:33], v156 offset:28672
	ds_read_b128 v[34:37], v156 offset:32768
	ds_read_b128 v[184:187], v156 offset:16
	ds_read_b128 v[188:191], v156 offset:4112
	ds_read_b128 v[192:195], v156 offset:8208
	ds_read_b128 v[196:199], v156 offset:12304
	ds_read_b128 v[200:203], v156 offset:16400
	ds_read_b128 v[204:207], v156 offset:20496
	ds_read_b128 v[208:211], v156 offset:24592
	ds_read_b128 v[212:215], v156 offset:28688
	ds_read_b128 v[216:219], v156 offset:32784
	s_waitcnt vmcnt(59) lgkmcnt(9)
	v_fmac_f32_e32 v144, v2, v60
	v_fmac_f32_e32 v145, v6, v60
	v_fmac_f32_e32 v146, v10, v60
	v_fmac_f32_e32 v147, v14, v60
	v_fmac_f32_e32 v148, v18, v60
	v_fmac_f32_e32 v149, v22, v60
	v_fmac_f32_e32 v150, v26, v60
	v_fmac_f32_e32 v151, v30, v60
	v_fmac_f32_e32 v152, v34, v60
	global_load_dword v60, v154, s[10:11]
	s_add_u32 s10, s10, 0x3000
	s_addc_u32 s11, s11, 0
	s_waitcnt vmcnt(59)
	v_fmac_f32_e32 v144, v3, v61
	v_fmac_f32_e32 v145, v7, v61
	v_fmac_f32_e32 v146, v11, v61
	v_fmac_f32_e32 v147, v15, v61
	v_fmac_f32_e32 v148, v19, v61
	v_fmac_f32_e32 v149, v23, v61
	v_fmac_f32_e32 v150, v27, v61
	v_fmac_f32_e32 v151, v31, v61
	v_fmac_f32_e32 v152, v35, v61
	global_load_dword v61, v154, s[10:11]
	s_add_u32 s10, s10, 0x3000
	s_addc_u32 s11, s11, 0
	s_waitcnt vmcnt(59)
	v_fmac_f32_e32 v144, v4, v62
	v_fmac_f32_e32 v145, v8, v62
	v_fmac_f32_e32 v146, v12, v62
	v_fmac_f32_e32 v147, v16, v62
	v_fmac_f32_e32 v148, v20, v62
	v_fmac_f32_e32 v149, v24, v62
	v_fmac_f32_e32 v150, v28, v62
	v_fmac_f32_e32 v151, v32, v62
	v_fmac_f32_e32 v152, v36, v62
	global_load_dword v62, v154, s[10:11]
	s_add_u32 s10, s10, 0x3000
	s_addc_u32 s11, s11, 0
	s_waitcnt vmcnt(59)
	v_fmac_f32_e32 v144, v5, v63
	v_fmac_f32_e32 v145, v9, v63
	v_fmac_f32_e32 v146, v13, v63
	v_fmac_f32_e32 v147, v17, v63
	v_fmac_f32_e32 v148, v21, v63
	v_fmac_f32_e32 v149, v25, v63
	v_fmac_f32_e32 v150, v29, v63
	v_fmac_f32_e32 v151, v33, v63
	v_fmac_f32_e32 v152, v37, v63
	global_load_dword v63, v154, s[10:11]
	s_add_u32 s10, s10, 0x3000
	s_addc_u32 s11, s11, 0
	ds_read_b128 v[2:5], v156 offset:32
	ds_read_b128 v[6:9], v156 offset:4128
	ds_read_b128 v[10:13], v156 offset:8224
	ds_read_b128 v[14:17], v156 offset:12320
	ds_read_b128 v[18:21], v156 offset:16416
	ds_read_b128 v[22:25], v156 offset:20512
	ds_read_b128 v[26:29], v156 offset:24608
	ds_read_b128 v[30:33], v156 offset:28704
	ds_read_b128 v[34:37], v156 offset:32800
	s_waitcnt vmcnt(59) lgkmcnt(9)
	v_fmac_f32_e32 v144, v184, v64
	v_fmac_f32_e32 v145, v188, v64
	v_fmac_f32_e32 v146, v192, v64
	v_fmac_f32_e32 v147, v196, v64
	v_fmac_f32_e32 v148, v200, v64
	v_fmac_f32_e32 v149, v204, v64
	v_fmac_f32_e32 v150, v208, v64
	v_fmac_f32_e32 v151, v212, v64
	v_fmac_f32_e32 v152, v216, v64
	global_load_dword v64, v154, s[10:11]
	s_add_u32 s10, s10, 0x3000
	s_addc_u32 s11, s11, 0
	s_waitcnt vmcnt(59)
	v_fmac_f32_e32 v144, v185, v65
	v_fmac_f32_e32 v145, v189, v65
	v_fmac_f32_e32 v146, v193, v65
	v_fmac_f32_e32 v147, v197, v65
	v_fmac_f32_e32 v148, v201, v65
	v_fmac_f32_e32 v149, v205, v65
	v_fmac_f32_e32 v150, v209, v65
	v_fmac_f32_e32 v151, v213, v65
	v_fmac_f32_e32 v152, v217, v65
	global_load_dword v65, v154, s[10:11]
	s_add_u32 s10, s10, 0x3000
	s_addc_u32 s11, s11, 0
	s_waitcnt vmcnt(59)
	v_fmac_f32_e32 v144, v186, v66
	v_fmac_f32_e32 v145, v190, v66
	v_fmac_f32_e32 v146, v194, v66
	v_fmac_f32_e32 v147, v198, v66
	v_fmac_f32_e32 v148, v202, v66
	v_fmac_f32_e32 v149, v206, v66
	v_fmac_f32_e32 v150, v210, v66
	v_fmac_f32_e32 v151, v214, v66
	v_fmac_f32_e32 v152, v218, v66
	global_load_dword v66, v154, s[10:11]
	s_add_u32 s10, s10, 0x3000
	s_addc_u32 s11, s11, 0
	s_waitcnt vmcnt(59)
	v_fmac_f32_e32 v144, v187, v67
	v_fmac_f32_e32 v145, v191, v67
	v_fmac_f32_e32 v146, v195, v67
	v_fmac_f32_e32 v147, v199, v67
	v_fmac_f32_e32 v148, v203, v67
	v_fmac_f32_e32 v149, v207, v67
	v_fmac_f32_e32 v150, v211, v67
	v_fmac_f32_e32 v151, v215, v67
	v_fmac_f32_e32 v152, v219, v67
	global_load_dword v67, v154, s[10:11]
	s_add_u32 s10, s10, 0x3000
	s_addc_u32 s11, s11, 0
	ds_read_b128 v[184:187], v156 offset:48
	ds_read_b128 v[188:191], v156 offset:4144
	ds_read_b128 v[192:195], v156 offset:8240
	ds_read_b128 v[196:199], v156 offset:12336
	ds_read_b128 v[200:203], v156 offset:16432
	ds_read_b128 v[204:207], v156 offset:20528
	ds_read_b128 v[208:211], v156 offset:24624
	ds_read_b128 v[212:215], v156 offset:28720
	ds_read_b128 v[216:219], v156 offset:32816
	s_waitcnt vmcnt(59) lgkmcnt(9)
	v_fmac_f32_e32 v144, v2, v68
	v_fmac_f32_e32 v145, v6, v68
	v_fmac_f32_e32 v146, v10, v68
	v_fmac_f32_e32 v147, v14, v68
	v_fmac_f32_e32 v148, v18, v68
	v_fmac_f32_e32 v149, v22, v68
	v_fmac_f32_e32 v150, v26, v68
	v_fmac_f32_e32 v151, v30, v68
	v_fmac_f32_e32 v152, v34, v68
	global_load_dword v68, v154, s[10:11]
	s_add_u32 s10, s10, 0x3000
	s_addc_u32 s11, s11, 0
	s_waitcnt vmcnt(59)
	v_fmac_f32_e32 v144, v3, v69
	v_fmac_f32_e32 v145, v7, v69
	v_fmac_f32_e32 v146, v11, v69
	v_fmac_f32_e32 v147, v15, v69
	v_fmac_f32_e32 v148, v19, v69
	v_fmac_f32_e32 v149, v23, v69
	v_fmac_f32_e32 v150, v27, v69
	v_fmac_f32_e32 v151, v31, v69
	v_fmac_f32_e32 v152, v35, v69
	global_load_dword v69, v154, s[10:11]
	s_add_u32 s10, s10, 0x3000
	s_addc_u32 s11, s11, 0
	s_waitcnt vmcnt(59)
	v_fmac_f32_e32 v144, v4, v70
	v_fmac_f32_e32 v145, v8, v70
	v_fmac_f32_e32 v146, v12, v70
	v_fmac_f32_e32 v147, v16, v70
	v_fmac_f32_e32 v148, v20, v70
	v_fmac_f32_e32 v149, v24, v70
	v_fmac_f32_e32 v150, v28, v70
	v_fmac_f32_e32 v151, v32, v70
	v_fmac_f32_e32 v152, v36, v70
	global_load_dword v70, v154, s[10:11]
	s_add_u32 s10, s10, 0x3000
	s_addc_u32 s11, s11, 0
	s_waitcnt vmcnt(59)
	v_fmac_f32_e32 v144, v5, v71
	v_fmac_f32_e32 v145, v9, v71
	v_fmac_f32_e32 v146, v13, v71
	v_fmac_f32_e32 v147, v17, v71
	v_fmac_f32_e32 v148, v21, v71
	v_fmac_f32_e32 v149, v25, v71
	v_fmac_f32_e32 v150, v29, v71
	v_fmac_f32_e32 v151, v33, v71
	v_fmac_f32_e32 v152, v37, v71
	global_load_dword v71, v154, s[10:11]
	s_add_u32 s10, s10, 0x3000
	s_addc_u32 s11, s11, 0
	ds_read_b128 v[2:5], v156 offset:64
	ds_read_b128 v[6:9], v156 offset:4160
	ds_read_b128 v[10:13], v156 offset:8256
	ds_read_b128 v[14:17], v156 offset:12352
	ds_read_b128 v[18:21], v156 offset:16448
	ds_read_b128 v[22:25], v156 offset:20544
	ds_read_b128 v[26:29], v156 offset:24640
	ds_read_b128 v[30:33], v156 offset:28736
	ds_read_b128 v[34:37], v156 offset:32832
	s_waitcnt vmcnt(59) lgkmcnt(9)
	v_fmac_f32_e32 v144, v184, v72
	v_fmac_f32_e32 v145, v188, v72
	v_fmac_f32_e32 v146, v192, v72
	v_fmac_f32_e32 v147, v196, v72
	v_fmac_f32_e32 v148, v200, v72
	v_fmac_f32_e32 v149, v204, v72
	v_fmac_f32_e32 v150, v208, v72
	v_fmac_f32_e32 v151, v212, v72
	v_fmac_f32_e32 v152, v216, v72
	global_load_dword v72, v154, s[10:11]
	s_add_u32 s10, s10, 0x3000
	s_addc_u32 s11, s11, 0
	s_waitcnt vmcnt(59)
	v_fmac_f32_e32 v144, v185, v73
	v_fmac_f32_e32 v145, v189, v73
	v_fmac_f32_e32 v146, v193, v73
	v_fmac_f32_e32 v147, v197, v73
	v_fmac_f32_e32 v148, v201, v73
	v_fmac_f32_e32 v149, v205, v73
	v_fmac_f32_e32 v150, v209, v73
	v_fmac_f32_e32 v151, v213, v73
	v_fmac_f32_e32 v152, v217, v73
	global_load_dword v73, v154, s[10:11]
	s_add_u32 s10, s10, 0x3000
	s_addc_u32 s11, s11, 0
	s_waitcnt vmcnt(59)
	v_fmac_f32_e32 v144, v186, v74
	v_fmac_f32_e32 v145, v190, v74
	v_fmac_f32_e32 v146, v194, v74
	v_fmac_f32_e32 v147, v198, v74
	v_fmac_f32_e32 v148, v202, v74
	v_fmac_f32_e32 v149, v206, v74
	v_fmac_f32_e32 v150, v210, v74
	v_fmac_f32_e32 v151, v214, v74
	v_fmac_f32_e32 v152, v218, v74
	global_load_dword v74, v154, s[10:11]
	s_add_u32 s10, s10, 0x3000
	s_addc_u32 s11, s11, 0
	s_waitcnt vmcnt(59)
	v_fmac_f32_e32 v144, v187, v75
	v_fmac_f32_e32 v145, v191, v75
	v_fmac_f32_e32 v146, v195, v75
	v_fmac_f32_e32 v147, v199, v75
	v_fmac_f32_e32 v148, v203, v75
	v_fmac_f32_e32 v149, v207, v75
	v_fmac_f32_e32 v150, v211, v75
	v_fmac_f32_e32 v151, v215, v75
	v_fmac_f32_e32 v152, v219, v75
	global_load_dword v75, v154, s[10:11]
	s_add_u32 s10, s10, 0x3000
	s_addc_u32 s11, s11, 0
	ds_read_b128 v[184:187], v156 offset:80
	ds_read_b128 v[188:191], v156 offset:4176
	ds_read_b128 v[192:195], v156 offset:8272
	ds_read_b128 v[196:199], v156 offset:12368
	ds_read_b128 v[200:203], v156 offset:16464
	ds_read_b128 v[204:207], v156 offset:20560
	ds_read_b128 v[208:211], v156 offset:24656
	ds_read_b128 v[212:215], v156 offset:28752
	ds_read_b128 v[216:219], v156 offset:32848
	s_waitcnt vmcnt(59) lgkmcnt(9)
	v_fmac_f32_e32 v144, v2, v76
	v_fmac_f32_e32 v145, v6, v76
	v_fmac_f32_e32 v146, v10, v76
	v_fmac_f32_e32 v147, v14, v76
	v_fmac_f32_e32 v148, v18, v76
	v_fmac_f32_e32 v149, v22, v76
	v_fmac_f32_e32 v150, v26, v76
	v_fmac_f32_e32 v151, v30, v76
	v_fmac_f32_e32 v152, v34, v76
	global_load_dword v76, v154, s[10:11]
	s_add_u32 s10, s10, 0x3000
	s_addc_u32 s11, s11, 0
	s_waitcnt vmcnt(59)
	v_fmac_f32_e32 v144, v3, v77
	v_fmac_f32_e32 v145, v7, v77
	v_fmac_f32_e32 v146, v11, v77
	v_fmac_f32_e32 v147, v15, v77
	v_fmac_f32_e32 v148, v19, v77
	v_fmac_f32_e32 v149, v23, v77
	v_fmac_f32_e32 v150, v27, v77
	v_fmac_f32_e32 v151, v31, v77
	v_fmac_f32_e32 v152, v35, v77
	global_load_dword v77, v154, s[10:11]
	s_add_u32 s10, s10, 0x3000
	s_addc_u32 s11, s11, 0
	s_waitcnt vmcnt(59)
	v_fmac_f32_e32 v144, v4, v78
	v_fmac_f32_e32 v145, v8, v78
	v_fmac_f32_e32 v146, v12, v78
	v_fmac_f32_e32 v147, v16, v78
	v_fmac_f32_e32 v148, v20, v78
	v_fmac_f32_e32 v149, v24, v78
	v_fmac_f32_e32 v150, v28, v78
	v_fmac_f32_e32 v151, v32, v78
	v_fmac_f32_e32 v152, v36, v78
	global_load_dword v78, v154, s[10:11]
	s_add_u32 s10, s10, 0x3000
	s_addc_u32 s11, s11, 0
	s_waitcnt vmcnt(59)
	v_fmac_f32_e32 v144, v5, v79
	v_fmac_f32_e32 v145, v9, v79
	v_fmac_f32_e32 v146, v13, v79
	v_fmac_f32_e32 v147, v17, v79
	v_fmac_f32_e32 v148, v21, v79
	v_fmac_f32_e32 v149, v25, v79
	v_fmac_f32_e32 v150, v29, v79
	v_fmac_f32_e32 v151, v33, v79
	v_fmac_f32_e32 v152, v37, v79
	global_load_dword v79, v154, s[10:11]
	s_add_u32 s10, s10, 0x3000
	s_addc_u32 s11, s11, 0
	ds_read_b128 v[2:5], v156 offset:96
	ds_read_b128 v[6:9], v156 offset:4192
	ds_read_b128 v[10:13], v156 offset:8288
	ds_read_b128 v[14:17], v156 offset:12384
	ds_read_b128 v[18:21], v156 offset:16480
	ds_read_b128 v[22:25], v156 offset:20576
	ds_read_b128 v[26:29], v156 offset:24672
	ds_read_b128 v[30:33], v156 offset:28768
	ds_read_b128 v[34:37], v156 offset:32864
	s_waitcnt vmcnt(59) lgkmcnt(9)
	v_fmac_f32_e32 v144, v184, v80
	v_fmac_f32_e32 v145, v188, v80
	v_fmac_f32_e32 v146, v192, v80
	v_fmac_f32_e32 v147, v196, v80
	v_fmac_f32_e32 v148, v200, v80
	v_fmac_f32_e32 v149, v204, v80
	v_fmac_f32_e32 v150, v208, v80
	v_fmac_f32_e32 v151, v212, v80
	v_fmac_f32_e32 v152, v216, v80
	global_load_dword v80, v154, s[10:11]
	s_add_u32 s10, s10, 0x3000
	s_addc_u32 s11, s11, 0
	s_waitcnt vmcnt(59)
	v_fmac_f32_e32 v144, v185, v81
	v_fmac_f32_e32 v145, v189, v81
	v_fmac_f32_e32 v146, v193, v81
	v_fmac_f32_e32 v147, v197, v81
	v_fmac_f32_e32 v148, v201, v81
	v_fmac_f32_e32 v149, v205, v81
	v_fmac_f32_e32 v150, v209, v81
	v_fmac_f32_e32 v151, v213, v81
	v_fmac_f32_e32 v152, v217, v81
	global_load_dword v81, v154, s[10:11]
	s_add_u32 s10, s10, 0x3000
	s_addc_u32 s11, s11, 0
	s_waitcnt vmcnt(59)
	v_fmac_f32_e32 v144, v186, v83
	v_fmac_f32_e32 v145, v190, v83
	v_fmac_f32_e32 v146, v194, v83
	v_fmac_f32_e32 v147, v198, v83
	v_fmac_f32_e32 v148, v202, v83
	v_fmac_f32_e32 v149, v206, v83
	v_fmac_f32_e32 v150, v210, v83
	v_fmac_f32_e32 v151, v214, v83
	v_fmac_f32_e32 v152, v218, v83
	global_load_dword v83, v154, s[10:11]
	s_add_u32 s10, s10, 0x3000
	s_addc_u32 s11, s11, 0
	s_waitcnt vmcnt(59)
	v_fmac_f32_e32 v144, v187, v84
	v_fmac_f32_e32 v145, v191, v84
	v_fmac_f32_e32 v146, v195, v84
	v_fmac_f32_e32 v147, v199, v84
	v_fmac_f32_e32 v148, v203, v84
	v_fmac_f32_e32 v149, v207, v84
	v_fmac_f32_e32 v150, v211, v84
	v_fmac_f32_e32 v151, v215, v84
	v_fmac_f32_e32 v152, v219, v84
	global_load_dword v84, v154, s[10:11]
	s_add_u32 s10, s10, 0x3000
	s_addc_u32 s11, s11, 0
	ds_read_b128 v[184:187], v156 offset:112
	ds_read_b128 v[188:191], v156 offset:4208
	ds_read_b128 v[192:195], v156 offset:8304
	ds_read_b128 v[196:199], v156 offset:12400
	ds_read_b128 v[200:203], v156 offset:16496
	ds_read_b128 v[204:207], v156 offset:20592
	ds_read_b128 v[208:211], v156 offset:24688
	ds_read_b128 v[212:215], v156 offset:28784
	ds_read_b128 v[216:219], v156 offset:32880
	s_waitcnt vmcnt(59) lgkmcnt(9)
	v_fmac_f32_e32 v144, v2, v85
	v_fmac_f32_e32 v145, v6, v85
	v_fmac_f32_e32 v146, v10, v85
	v_fmac_f32_e32 v147, v14, v85
	v_fmac_f32_e32 v148, v18, v85
	v_fmac_f32_e32 v149, v22, v85
	v_fmac_f32_e32 v150, v26, v85
	v_fmac_f32_e32 v151, v30, v85
	v_fmac_f32_e32 v152, v34, v85
	global_load_dword v85, v154, s[10:11]
	s_add_u32 s10, s10, 0x3000
	s_addc_u32 s11, s11, 0
	s_waitcnt vmcnt(59)
	v_fmac_f32_e32 v144, v3, v86
	v_fmac_f32_e32 v145, v7, v86
	v_fmac_f32_e32 v146, v11, v86
	v_fmac_f32_e32 v147, v15, v86
	v_fmac_f32_e32 v148, v19, v86
	v_fmac_f32_e32 v149, v23, v86
	v_fmac_f32_e32 v150, v27, v86
	v_fmac_f32_e32 v151, v31, v86
	v_fmac_f32_e32 v152, v35, v86
	global_load_dword v86, v154, s[10:11]
	s_add_u32 s10, s10, 0x3000
	s_addc_u32 s11, s11, 0
	s_waitcnt vmcnt(59)
	v_fmac_f32_e32 v144, v4, v87
	v_fmac_f32_e32 v145, v8, v87
	v_fmac_f32_e32 v146, v12, v87
	v_fmac_f32_e32 v147, v16, v87
	v_fmac_f32_e32 v148, v20, v87
	v_fmac_f32_e32 v149, v24, v87
	v_fmac_f32_e32 v150, v28, v87
	v_fmac_f32_e32 v151, v32, v87
	v_fmac_f32_e32 v152, v36, v87
	global_load_dword v87, v154, s[10:11]
	s_add_u32 s10, s10, 0x3000
	s_addc_u32 s11, s11, 0
	s_waitcnt vmcnt(59)
	v_fmac_f32_e32 v144, v5, v88
	v_fmac_f32_e32 v145, v9, v88
	v_fmac_f32_e32 v146, v13, v88
	v_fmac_f32_e32 v147, v17, v88
	v_fmac_f32_e32 v148, v21, v88
	v_fmac_f32_e32 v149, v25, v88
	v_fmac_f32_e32 v150, v29, v88
	v_fmac_f32_e32 v151, v33, v88
	v_fmac_f32_e32 v152, v37, v88
	global_load_dword v88, v154, s[10:11]
	s_add_u32 s10, s10, 0x3000
	s_addc_u32 s11, s11, 0
	ds_read_b128 v[2:5], v156 offset:128
	ds_read_b128 v[6:9], v156 offset:4224
	ds_read_b128 v[10:13], v156 offset:8320
	ds_read_b128 v[14:17], v156 offset:12416
	ds_read_b128 v[18:21], v156 offset:16512
	ds_read_b128 v[22:25], v156 offset:20608
	ds_read_b128 v[26:29], v156 offset:24704
	ds_read_b128 v[30:33], v156 offset:28800
	ds_read_b128 v[34:37], v156 offset:32896
	s_waitcnt vmcnt(59) lgkmcnt(9)
	v_fmac_f32_e32 v144, v184, v89
	v_fmac_f32_e32 v145, v188, v89
	v_fmac_f32_e32 v146, v192, v89
	v_fmac_f32_e32 v147, v196, v89
	v_fmac_f32_e32 v148, v200, v89
	v_fmac_f32_e32 v149, v204, v89
	v_fmac_f32_e32 v150, v208, v89
	v_fmac_f32_e32 v151, v212, v89
	v_fmac_f32_e32 v152, v216, v89
	global_load_dword v89, v154, s[10:11]
	s_add_u32 s10, s10, 0x3000
	s_addc_u32 s11, s11, 0
	s_waitcnt vmcnt(59)
	v_fmac_f32_e32 v144, v185, v90
	v_fmac_f32_e32 v145, v189, v90
	v_fmac_f32_e32 v146, v193, v90
	v_fmac_f32_e32 v147, v197, v90
	v_fmac_f32_e32 v148, v201, v90
	v_fmac_f32_e32 v149, v205, v90
	v_fmac_f32_e32 v150, v209, v90
	v_fmac_f32_e32 v151, v213, v90
	v_fmac_f32_e32 v152, v217, v90
	global_load_dword v90, v154, s[10:11]
	s_add_u32 s10, s10, 0x3000
	s_addc_u32 s11, s11, 0
	s_waitcnt vmcnt(59)
	v_fmac_f32_e32 v144, v186, v91
	v_fmac_f32_e32 v145, v190, v91
	v_fmac_f32_e32 v146, v194, v91
	v_fmac_f32_e32 v147, v198, v91
	v_fmac_f32_e32 v148, v202, v91
	v_fmac_f32_e32 v149, v206, v91
	v_fmac_f32_e32 v150, v210, v91
	v_fmac_f32_e32 v151, v214, v91
	v_fmac_f32_e32 v152, v218, v91
	global_load_dword v91, v154, s[10:11]
	s_add_u32 s10, s10, 0x3000
	s_addc_u32 s11, s11, 0
	s_waitcnt vmcnt(59)
	v_fmac_f32_e32 v144, v187, v92
	v_fmac_f32_e32 v145, v191, v92
	v_fmac_f32_e32 v146, v195, v92
	v_fmac_f32_e32 v147, v199, v92
	v_fmac_f32_e32 v148, v203, v92
	v_fmac_f32_e32 v149, v207, v92
	v_fmac_f32_e32 v150, v211, v92
	v_fmac_f32_e32 v151, v215, v92
	v_fmac_f32_e32 v152, v219, v92
	global_load_dword v92, v154, s[10:11]
	s_add_u32 s10, s10, 0x3000
	s_addc_u32 s11, s11, 0
	ds_read_b128 v[184:187], v156 offset:144
	ds_read_b128 v[188:191], v156 offset:4240
	ds_read_b128 v[192:195], v156 offset:8336
	ds_read_b128 v[196:199], v156 offset:12432
	ds_read_b128 v[200:203], v156 offset:16528
	ds_read_b128 v[204:207], v156 offset:20624
	ds_read_b128 v[208:211], v156 offset:24720
	ds_read_b128 v[212:215], v156 offset:28816
	ds_read_b128 v[216:219], v156 offset:32912
	s_waitcnt vmcnt(59) lgkmcnt(9)
	v_fmac_f32_e32 v144, v2, v93
	v_fmac_f32_e32 v145, v6, v93
	v_fmac_f32_e32 v146, v10, v93
	v_fmac_f32_e32 v147, v14, v93
	v_fmac_f32_e32 v148, v18, v93
	v_fmac_f32_e32 v149, v22, v93
	v_fmac_f32_e32 v150, v26, v93
	v_fmac_f32_e32 v151, v30, v93
	v_fmac_f32_e32 v152, v34, v93
	global_load_dword v93, v154, s[10:11]
	s_add_u32 s10, s10, 0x3000
	s_addc_u32 s11, s11, 0
	s_waitcnt vmcnt(59)
	v_fmac_f32_e32 v144, v3, v94
	v_fmac_f32_e32 v145, v7, v94
	v_fmac_f32_e32 v146, v11, v94
	v_fmac_f32_e32 v147, v15, v94
	v_fmac_f32_e32 v148, v19, v94
	v_fmac_f32_e32 v149, v23, v94
	v_fmac_f32_e32 v150, v27, v94
	v_fmac_f32_e32 v151, v31, v94
	v_fmac_f32_e32 v152, v35, v94
	global_load_dword v94, v154, s[10:11]
	s_add_u32 s10, s10, 0x3000
	s_addc_u32 s11, s11, 0
	s_waitcnt vmcnt(59)
	v_fmac_f32_e32 v144, v4, v95
	v_fmac_f32_e32 v145, v8, v95
	v_fmac_f32_e32 v146, v12, v95
	v_fmac_f32_e32 v147, v16, v95
	v_fmac_f32_e32 v148, v20, v95
	v_fmac_f32_e32 v149, v24, v95
	v_fmac_f32_e32 v150, v28, v95
	v_fmac_f32_e32 v151, v32, v95
	v_fmac_f32_e32 v152, v36, v95
	global_load_dword v95, v154, s[10:11]
	s_add_u32 s10, s10, 0x3000
	s_addc_u32 s11, s11, 0
	s_waitcnt vmcnt(59)
	v_fmac_f32_e32 v144, v5, v96
	v_fmac_f32_e32 v145, v9, v96
	v_fmac_f32_e32 v146, v13, v96
	v_fmac_f32_e32 v147, v17, v96
	v_fmac_f32_e32 v148, v21, v96
	v_fmac_f32_e32 v149, v25, v96
	v_fmac_f32_e32 v150, v29, v96
	v_fmac_f32_e32 v151, v33, v96
	v_fmac_f32_e32 v152, v37, v96
	global_load_dword v96, v154, s[10:11]
	s_add_u32 s10, s10, 0x3000
	s_addc_u32 s11, s11, 0
	ds_read_b128 v[2:5], v156 offset:160
	ds_read_b128 v[6:9], v156 offset:4256
	ds_read_b128 v[10:13], v156 offset:8352
	ds_read_b128 v[14:17], v156 offset:12448
	ds_read_b128 v[18:21], v156 offset:16544
	ds_read_b128 v[22:25], v156 offset:20640
	ds_read_b128 v[26:29], v156 offset:24736
	ds_read_b128 v[30:33], v156 offset:28832
	ds_read_b128 v[34:37], v156 offset:32928
	s_waitcnt vmcnt(59) lgkmcnt(9)
	v_fmac_f32_e32 v144, v184, v97
	v_fmac_f32_e32 v145, v188, v97
	v_fmac_f32_e32 v146, v192, v97
	v_fmac_f32_e32 v147, v196, v97
	v_fmac_f32_e32 v148, v200, v97
	v_fmac_f32_e32 v149, v204, v97
	v_fmac_f32_e32 v150, v208, v97
	v_fmac_f32_e32 v151, v212, v97
	v_fmac_f32_e32 v152, v216, v97
	global_load_dword v97, v154, s[10:11]
	s_add_u32 s10, s10, 0x3000
	s_addc_u32 s11, s11, 0
	s_waitcnt vmcnt(59)
	v_fmac_f32_e32 v144, v185, v98
	v_fmac_f32_e32 v145, v189, v98
	v_fmac_f32_e32 v146, v193, v98
	v_fmac_f32_e32 v147, v197, v98
	v_fmac_f32_e32 v148, v201, v98
	v_fmac_f32_e32 v149, v205, v98
	v_fmac_f32_e32 v150, v209, v98
	v_fmac_f32_e32 v151, v213, v98
	v_fmac_f32_e32 v152, v217, v98
	global_load_dword v98, v154, s[10:11]
	s_add_u32 s10, s10, 0x3000
	s_addc_u32 s11, s11, 0
	s_waitcnt vmcnt(59)
	v_fmac_f32_e32 v144, v186, v99
	v_fmac_f32_e32 v145, v190, v99
	v_fmac_f32_e32 v146, v194, v99
	v_fmac_f32_e32 v147, v198, v99
	v_fmac_f32_e32 v148, v202, v99
	v_fmac_f32_e32 v149, v206, v99
	v_fmac_f32_e32 v150, v210, v99
	v_fmac_f32_e32 v151, v214, v99
	v_fmac_f32_e32 v152, v218, v99
	global_load_dword v99, v154, s[10:11]
	s_add_u32 s10, s10, 0x3000
	s_addc_u32 s11, s11, 0
	s_waitcnt vmcnt(59)
	v_fmac_f32_e32 v144, v187, v100
	v_fmac_f32_e32 v145, v191, v100
	v_fmac_f32_e32 v146, v195, v100
	v_fmac_f32_e32 v147, v199, v100
	v_fmac_f32_e32 v148, v203, v100
	v_fmac_f32_e32 v149, v207, v100
	v_fmac_f32_e32 v150, v211, v100
	v_fmac_f32_e32 v151, v215, v100
	v_fmac_f32_e32 v152, v219, v100
	global_load_dword v100, v154, s[10:11]
	s_add_u32 s10, s10, 0x3000
	s_addc_u32 s11, s11, 0
	ds_read_b128 v[184:187], v156 offset:176
	ds_read_b128 v[188:191], v156 offset:4272
	ds_read_b128 v[192:195], v156 offset:8368
	ds_read_b128 v[196:199], v156 offset:12464
	ds_read_b128 v[200:203], v156 offset:16560
	ds_read_b128 v[204:207], v156 offset:20656
	ds_read_b128 v[208:211], v156 offset:24752
	ds_read_b128 v[212:215], v156 offset:28848
	ds_read_b128 v[216:219], v156 offset:32944
	s_waitcnt vmcnt(59) lgkmcnt(9)
	v_fmac_f32_e32 v144, v2, v101
	v_fmac_f32_e32 v145, v6, v101
	v_fmac_f32_e32 v146, v10, v101
	v_fmac_f32_e32 v147, v14, v101
	v_fmac_f32_e32 v148, v18, v101
	v_fmac_f32_e32 v149, v22, v101
	v_fmac_f32_e32 v150, v26, v101
	v_fmac_f32_e32 v151, v30, v101
	v_fmac_f32_e32 v152, v34, v101
	global_load_dword v101, v154, s[10:11]
	s_add_u32 s10, s10, 0x3000
	s_addc_u32 s11, s11, 0
	s_waitcnt vmcnt(59)
	v_fmac_f32_e32 v144, v3, v102
	v_fmac_f32_e32 v145, v7, v102
	v_fmac_f32_e32 v146, v11, v102
	v_fmac_f32_e32 v147, v15, v102
	v_fmac_f32_e32 v148, v19, v102
	v_fmac_f32_e32 v149, v23, v102
	v_fmac_f32_e32 v150, v27, v102
	v_fmac_f32_e32 v151, v31, v102
	v_fmac_f32_e32 v152, v35, v102
	global_load_dword v102, v154, s[10:11]
	s_add_u32 s10, s10, 0x3000
	s_addc_u32 s11, s11, 0
	s_waitcnt vmcnt(59)
	v_fmac_f32_e32 v144, v4, v103
	v_fmac_f32_e32 v145, v8, v103
	v_fmac_f32_e32 v146, v12, v103
	v_fmac_f32_e32 v147, v16, v103
	v_fmac_f32_e32 v148, v20, v103
	v_fmac_f32_e32 v149, v24, v103
	v_fmac_f32_e32 v150, v28, v103
	v_fmac_f32_e32 v151, v32, v103
	v_fmac_f32_e32 v152, v36, v103
	global_load_dword v103, v154, s[10:11]
	s_add_u32 s10, s10, 0x3000
	s_addc_u32 s11, s11, 0
	s_waitcnt vmcnt(59)
	v_fmac_f32_e32 v144, v5, v104
	v_fmac_f32_e32 v145, v9, v104
	v_fmac_f32_e32 v146, v13, v104
	v_fmac_f32_e32 v147, v17, v104
	v_fmac_f32_e32 v148, v21, v104
	v_fmac_f32_e32 v149, v25, v104
	v_fmac_f32_e32 v150, v29, v104
	v_fmac_f32_e32 v151, v33, v104
	v_fmac_f32_e32 v152, v37, v104
	global_load_dword v104, v154, s[10:11]
	s_add_u32 s10, s10, 0x3000
	s_addc_u32 s11, s11, 0
	ds_read_b128 v[2:5], v156 offset:192
	ds_read_b128 v[6:9], v156 offset:4288
	ds_read_b128 v[10:13], v156 offset:8384
	ds_read_b128 v[14:17], v156 offset:12480
	ds_read_b128 v[18:21], v156 offset:16576
	ds_read_b128 v[22:25], v156 offset:20672
	ds_read_b128 v[26:29], v156 offset:24768
	ds_read_b128 v[30:33], v156 offset:28864
	ds_read_b128 v[34:37], v156 offset:32960
	s_waitcnt vmcnt(59) lgkmcnt(9)
	v_fmac_f32_e32 v144, v184, v105
	v_fmac_f32_e32 v145, v188, v105
	v_fmac_f32_e32 v146, v192, v105
	v_fmac_f32_e32 v147, v196, v105
	v_fmac_f32_e32 v148, v200, v105
	v_fmac_f32_e32 v149, v204, v105
	v_fmac_f32_e32 v150, v208, v105
	v_fmac_f32_e32 v151, v212, v105
	v_fmac_f32_e32 v152, v216, v105
	global_load_dword v105, v154, s[10:11]
	s_add_u32 s10, s10, 0x3000
	s_addc_u32 s11, s11, 0
	s_waitcnt vmcnt(59)
	v_fmac_f32_e32 v144, v185, v106
	v_fmac_f32_e32 v145, v189, v106
	v_fmac_f32_e32 v146, v193, v106
	v_fmac_f32_e32 v147, v197, v106
	v_fmac_f32_e32 v148, v201, v106
	v_fmac_f32_e32 v149, v205, v106
	v_fmac_f32_e32 v150, v209, v106
	v_fmac_f32_e32 v151, v213, v106
	v_fmac_f32_e32 v152, v217, v106
	global_load_dword v106, v154, s[10:11]
	s_add_u32 s10, s10, 0x3000
	s_addc_u32 s11, s11, 0
	s_waitcnt vmcnt(59)
	v_fmac_f32_e32 v144, v186, v107
	v_fmac_f32_e32 v145, v190, v107
	v_fmac_f32_e32 v146, v194, v107
	v_fmac_f32_e32 v147, v198, v107
	v_fmac_f32_e32 v148, v202, v107
	v_fmac_f32_e32 v149, v206, v107
	v_fmac_f32_e32 v150, v210, v107
	v_fmac_f32_e32 v151, v214, v107
	v_fmac_f32_e32 v152, v218, v107
	global_load_dword v107, v154, s[10:11]
	s_add_u32 s10, s10, 0x3000
	s_addc_u32 s11, s11, 0
	s_waitcnt vmcnt(59)
	v_fmac_f32_e32 v144, v187, v108
	v_fmac_f32_e32 v145, v191, v108
	v_fmac_f32_e32 v146, v195, v108
	v_fmac_f32_e32 v147, v199, v108
	v_fmac_f32_e32 v148, v203, v108
	v_fmac_f32_e32 v149, v207, v108
	v_fmac_f32_e32 v150, v211, v108
	v_fmac_f32_e32 v151, v215, v108
	v_fmac_f32_e32 v152, v219, v108
	global_load_dword v108, v154, s[10:11]
	s_add_u32 s10, s10, 0x3000
	s_addc_u32 s11, s11, 0
	ds_read_b128 v[184:187], v156 offset:208
	ds_read_b128 v[188:191], v156 offset:4304
	ds_read_b128 v[192:195], v156 offset:8400
	ds_read_b128 v[196:199], v156 offset:12496
	ds_read_b128 v[200:203], v156 offset:16592
	ds_read_b128 v[204:207], v156 offset:20688
	ds_read_b128 v[208:211], v156 offset:24784
	ds_read_b128 v[212:215], v156 offset:28880
	ds_read_b128 v[216:219], v156 offset:32976
	s_waitcnt vmcnt(59) lgkmcnt(9)
	v_fmac_f32_e32 v144, v2, v109
	v_fmac_f32_e32 v145, v6, v109
	v_fmac_f32_e32 v146, v10, v109
	v_fmac_f32_e32 v147, v14, v109
	v_fmac_f32_e32 v148, v18, v109
	v_fmac_f32_e32 v149, v22, v109
	v_fmac_f32_e32 v150, v26, v109
	v_fmac_f32_e32 v151, v30, v109
	v_fmac_f32_e32 v152, v34, v109
	global_load_dword v109, v154, s[10:11]
	s_add_u32 s10, s10, 0x3000
	s_addc_u32 s11, s11, 0
	s_waitcnt vmcnt(59)
	v_fmac_f32_e32 v144, v3, v110
	v_fmac_f32_e32 v145, v7, v110
	v_fmac_f32_e32 v146, v11, v110
	v_fmac_f32_e32 v147, v15, v110
	v_fmac_f32_e32 v148, v19, v110
	v_fmac_f32_e32 v149, v23, v110
	v_fmac_f32_e32 v150, v27, v110
	v_fmac_f32_e32 v151, v31, v110
	v_fmac_f32_e32 v152, v35, v110
	global_load_dword v110, v154, s[10:11]
	s_add_u32 s10, s10, 0x3000
	s_addc_u32 s11, s11, 0
	s_waitcnt vmcnt(59)
	v_fmac_f32_e32 v144, v4, v111
	v_fmac_f32_e32 v145, v8, v111
	v_fmac_f32_e32 v146, v12, v111
	v_fmac_f32_e32 v147, v16, v111
	v_fmac_f32_e32 v148, v20, v111
	v_fmac_f32_e32 v149, v24, v111
	v_fmac_f32_e32 v150, v28, v111
	v_fmac_f32_e32 v151, v32, v111
	v_fmac_f32_e32 v152, v36, v111
	global_load_dword v111, v154, s[10:11]
	s_add_u32 s10, s10, 0x3000
	s_addc_u32 s11, s11, 0
	s_waitcnt vmcnt(59)
	v_fmac_f32_e32 v144, v5, v112
	v_fmac_f32_e32 v145, v9, v112
	v_fmac_f32_e32 v146, v13, v112
	v_fmac_f32_e32 v147, v17, v112
	v_fmac_f32_e32 v148, v21, v112
	v_fmac_f32_e32 v149, v25, v112
	v_fmac_f32_e32 v150, v29, v112
	v_fmac_f32_e32 v151, v33, v112
	v_fmac_f32_e32 v152, v37, v112
	global_load_dword v112, v154, s[10:11]
	s_add_u32 s10, s10, 0x3000
	s_addc_u32 s11, s11, 0
	ds_read_b128 v[2:5], v156 offset:224
	ds_read_b128 v[6:9], v156 offset:4320
	ds_read_b128 v[10:13], v156 offset:8416
	ds_read_b128 v[14:17], v156 offset:12512
	ds_read_b128 v[18:21], v156 offset:16608
	ds_read_b128 v[22:25], v156 offset:20704
	ds_read_b128 v[26:29], v156 offset:24800
	ds_read_b128 v[30:33], v156 offset:28896
	ds_read_b128 v[34:37], v156 offset:32992
	s_waitcnt vmcnt(59) lgkmcnt(9)
	v_fmac_f32_e32 v144, v184, v113
	v_fmac_f32_e32 v145, v188, v113
	v_fmac_f32_e32 v146, v192, v113
	v_fmac_f32_e32 v147, v196, v113
	v_fmac_f32_e32 v148, v200, v113
	v_fmac_f32_e32 v149, v204, v113
	v_fmac_f32_e32 v150, v208, v113
	v_fmac_f32_e32 v151, v212, v113
	v_fmac_f32_e32 v152, v216, v113
	global_load_dword v113, v154, s[10:11]
	s_add_u32 s10, s10, 0x3000
	s_addc_u32 s11, s11, 0
	s_waitcnt vmcnt(59)
	v_fmac_f32_e32 v144, v185, v114
	v_fmac_f32_e32 v145, v189, v114
	v_fmac_f32_e32 v146, v193, v114
	v_fmac_f32_e32 v147, v197, v114
	v_fmac_f32_e32 v148, v201, v114
	v_fmac_f32_e32 v149, v205, v114
	v_fmac_f32_e32 v150, v209, v114
	v_fmac_f32_e32 v151, v213, v114
	v_fmac_f32_e32 v152, v217, v114
	global_load_dword v114, v154, s[10:11]
	s_add_u32 s10, s10, 0x3000
	s_addc_u32 s11, s11, 0
	s_waitcnt vmcnt(59)
	v_fmac_f32_e32 v144, v186, v115
	v_fmac_f32_e32 v145, v190, v115
	v_fmac_f32_e32 v146, v194, v115
	v_fmac_f32_e32 v147, v198, v115
	v_fmac_f32_e32 v148, v202, v115
	v_fmac_f32_e32 v149, v206, v115
	v_fmac_f32_e32 v150, v210, v115
	v_fmac_f32_e32 v151, v214, v115
	v_fmac_f32_e32 v152, v218, v115
	global_load_dword v115, v154, s[10:11]
	s_add_u32 s10, s10, 0x3000
	s_addc_u32 s11, s11, 0
	s_waitcnt vmcnt(59)
	v_fmac_f32_e32 v144, v187, v116
	v_fmac_f32_e32 v145, v191, v116
	v_fmac_f32_e32 v146, v195, v116
	v_fmac_f32_e32 v147, v199, v116
	v_fmac_f32_e32 v148, v203, v116
	v_fmac_f32_e32 v149, v207, v116
	v_fmac_f32_e32 v150, v211, v116
	v_fmac_f32_e32 v151, v215, v116
	v_fmac_f32_e32 v152, v219, v116
	global_load_dword v116, v154, s[10:11]
	s_add_u32 s10, s10, 0x3000
	s_addc_u32 s11, s11, 0
	ds_read_b128 v[184:187], v156 offset:240
	ds_read_b128 v[188:191], v156 offset:4336
	ds_read_b128 v[192:195], v156 offset:8432
	ds_read_b128 v[196:199], v156 offset:12528
	ds_read_b128 v[200:203], v156 offset:16624
	ds_read_b128 v[204:207], v156 offset:20720
	ds_read_b128 v[208:211], v156 offset:24816
	ds_read_b128 v[212:215], v156 offset:28912
	ds_read_b128 v[216:219], v156 offset:33008
	s_waitcnt vmcnt(59) lgkmcnt(9)
	v_fmac_f32_e32 v144, v2, v117
	v_fmac_f32_e32 v145, v6, v117
	v_fmac_f32_e32 v146, v10, v117
	v_fmac_f32_e32 v147, v14, v117
	v_fmac_f32_e32 v148, v18, v117
	v_fmac_f32_e32 v149, v22, v117
	v_fmac_f32_e32 v150, v26, v117
	v_fmac_f32_e32 v151, v30, v117
	v_fmac_f32_e32 v152, v34, v117
	global_load_dword v117, v154, s[10:11]
	s_add_u32 s10, s10, 0x3000
	s_addc_u32 s11, s11, 0
	s_waitcnt vmcnt(59)
	v_fmac_f32_e32 v144, v3, v118
	v_fmac_f32_e32 v145, v7, v118
	v_fmac_f32_e32 v146, v11, v118
	v_fmac_f32_e32 v147, v15, v118
	v_fmac_f32_e32 v148, v19, v118
	v_fmac_f32_e32 v149, v23, v118
	v_fmac_f32_e32 v150, v27, v118
	v_fmac_f32_e32 v151, v31, v118
	v_fmac_f32_e32 v152, v35, v118
	global_load_dword v118, v154, s[10:11]
	s_add_u32 s10, s10, 0x3000
	s_addc_u32 s11, s11, 0
	s_waitcnt vmcnt(59)
	v_fmac_f32_e32 v144, v4, v119
	v_fmac_f32_e32 v145, v8, v119
	v_fmac_f32_e32 v146, v12, v119
	v_fmac_f32_e32 v147, v16, v119
	v_fmac_f32_e32 v148, v20, v119
	v_fmac_f32_e32 v149, v24, v119
	v_fmac_f32_e32 v150, v28, v119
	v_fmac_f32_e32 v151, v32, v119
	v_fmac_f32_e32 v152, v36, v119
	global_load_dword v119, v154, s[10:11]
	s_add_u32 s10, s10, 0x3000
	s_addc_u32 s11, s11, 0
	s_waitcnt vmcnt(59)
	v_fmac_f32_e32 v144, v5, v120
	v_fmac_f32_e32 v145, v9, v120
	v_fmac_f32_e32 v146, v13, v120
	v_fmac_f32_e32 v147, v17, v120
	v_fmac_f32_e32 v148, v21, v120
	v_fmac_f32_e32 v149, v25, v120
	v_fmac_f32_e32 v150, v29, v120
	v_fmac_f32_e32 v151, v33, v120
	v_fmac_f32_e32 v152, v37, v120
	global_load_dword v120, v154, s[10:11]
	s_add_u32 s10, s10, 0x3000
	s_addc_u32 s11, s11, 0
	ds_read_b128 v[2:5], v156 offset:256
	ds_read_b128 v[6:9], v156 offset:4352
	ds_read_b128 v[10:13], v156 offset:8448
	ds_read_b128 v[14:17], v156 offset:12544
	ds_read_b128 v[18:21], v156 offset:16640
	ds_read_b128 v[22:25], v156 offset:20736
	ds_read_b128 v[26:29], v156 offset:24832
	ds_read_b128 v[30:33], v156 offset:28928
	ds_read_b128 v[34:37], v156 offset:33024
	s_waitcnt vmcnt(59) lgkmcnt(9)
	v_fmac_f32_e32 v144, v184, v60
	v_fmac_f32_e32 v145, v188, v60
	v_fmac_f32_e32 v146, v192, v60
	v_fmac_f32_e32 v147, v196, v60
	v_fmac_f32_e32 v148, v200, v60
	v_fmac_f32_e32 v149, v204, v60
	v_fmac_f32_e32 v150, v208, v60
	v_fmac_f32_e32 v151, v212, v60
	v_fmac_f32_e32 v152, v216, v60
	global_load_dword v60, v154, s[10:11]
	s_add_u32 s10, s10, 0x3000
	s_addc_u32 s11, s11, 0
	s_waitcnt vmcnt(59)
	v_fmac_f32_e32 v144, v185, v61
	v_fmac_f32_e32 v145, v189, v61
	v_fmac_f32_e32 v146, v193, v61
	v_fmac_f32_e32 v147, v197, v61
	v_fmac_f32_e32 v148, v201, v61
	v_fmac_f32_e32 v149, v205, v61
	v_fmac_f32_e32 v150, v209, v61
	v_fmac_f32_e32 v151, v213, v61
	v_fmac_f32_e32 v152, v217, v61
	global_load_dword v61, v154, s[10:11]
	s_add_u32 s10, s10, 0x3000
	s_addc_u32 s11, s11, 0
	s_waitcnt vmcnt(59)
	v_fmac_f32_e32 v144, v186, v62
	v_fmac_f32_e32 v145, v190, v62
	v_fmac_f32_e32 v146, v194, v62
	v_fmac_f32_e32 v147, v198, v62
	v_fmac_f32_e32 v148, v202, v62
	v_fmac_f32_e32 v149, v206, v62
	v_fmac_f32_e32 v150, v210, v62
	v_fmac_f32_e32 v151, v214, v62
	v_fmac_f32_e32 v152, v218, v62
	global_load_dword v62, v154, s[10:11]
	s_add_u32 s10, s10, 0x3000
	s_addc_u32 s11, s11, 0
	s_waitcnt vmcnt(59)
	v_fmac_f32_e32 v144, v187, v63
	v_fmac_f32_e32 v145, v191, v63
	v_fmac_f32_e32 v146, v195, v63
	v_fmac_f32_e32 v147, v199, v63
	v_fmac_f32_e32 v148, v203, v63
	v_fmac_f32_e32 v149, v207, v63
	v_fmac_f32_e32 v150, v211, v63
	v_fmac_f32_e32 v151, v215, v63
	v_fmac_f32_e32 v152, v219, v63
	global_load_dword v63, v154, s[10:11]
	s_add_u32 s10, s10, 0x3000
	s_addc_u32 s11, s11, 0
	ds_read_b128 v[184:187], v156 offset:272
	ds_read_b128 v[188:191], v156 offset:4368
	ds_read_b128 v[192:195], v156 offset:8464
	ds_read_b128 v[196:199], v156 offset:12560
	ds_read_b128 v[200:203], v156 offset:16656
	ds_read_b128 v[204:207], v156 offset:20752
	ds_read_b128 v[208:211], v156 offset:24848
	ds_read_b128 v[212:215], v156 offset:28944
	ds_read_b128 v[216:219], v156 offset:33040
	s_waitcnt vmcnt(59) lgkmcnt(9)
	v_fmac_f32_e32 v144, v2, v64
	v_fmac_f32_e32 v145, v6, v64
	v_fmac_f32_e32 v146, v10, v64
	v_fmac_f32_e32 v147, v14, v64
	v_fmac_f32_e32 v148, v18, v64
	v_fmac_f32_e32 v149, v22, v64
	v_fmac_f32_e32 v150, v26, v64
	v_fmac_f32_e32 v151, v30, v64
	v_fmac_f32_e32 v152, v34, v64
	global_load_dword v64, v154, s[10:11]
	s_add_u32 s10, s10, 0x3000
	s_addc_u32 s11, s11, 0
	s_waitcnt vmcnt(59)
	v_fmac_f32_e32 v144, v3, v65
	v_fmac_f32_e32 v145, v7, v65
	v_fmac_f32_e32 v146, v11, v65
	v_fmac_f32_e32 v147, v15, v65
	v_fmac_f32_e32 v148, v19, v65
	v_fmac_f32_e32 v149, v23, v65
	v_fmac_f32_e32 v150, v27, v65
	v_fmac_f32_e32 v151, v31, v65
	v_fmac_f32_e32 v152, v35, v65
	global_load_dword v65, v154, s[10:11]
	s_add_u32 s10, s10, 0x3000
	s_addc_u32 s11, s11, 0
	s_waitcnt vmcnt(59)
	v_fmac_f32_e32 v144, v4, v66
	v_fmac_f32_e32 v145, v8, v66
	v_fmac_f32_e32 v146, v12, v66
	v_fmac_f32_e32 v147, v16, v66
	v_fmac_f32_e32 v148, v20, v66
	v_fmac_f32_e32 v149, v24, v66
	v_fmac_f32_e32 v150, v28, v66
	v_fmac_f32_e32 v151, v32, v66
	v_fmac_f32_e32 v152, v36, v66
	global_load_dword v66, v154, s[10:11]
	s_add_u32 s10, s10, 0x3000
	s_addc_u32 s11, s11, 0
	s_waitcnt vmcnt(59)
	v_fmac_f32_e32 v144, v5, v67
	v_fmac_f32_e32 v145, v9, v67
	v_fmac_f32_e32 v146, v13, v67
	v_fmac_f32_e32 v147, v17, v67
	v_fmac_f32_e32 v148, v21, v67
	v_fmac_f32_e32 v149, v25, v67
	v_fmac_f32_e32 v150, v29, v67
	v_fmac_f32_e32 v151, v33, v67
	v_fmac_f32_e32 v152, v37, v67
	global_load_dword v67, v154, s[10:11]
	s_add_u32 s10, s10, 0x3000
	s_addc_u32 s11, s11, 0
	ds_read_b128 v[2:5], v156 offset:288
	ds_read_b128 v[6:9], v156 offset:4384
	ds_read_b128 v[10:13], v156 offset:8480
	ds_read_b128 v[14:17], v156 offset:12576
	ds_read_b128 v[18:21], v156 offset:16672
	ds_read_b128 v[22:25], v156 offset:20768
	ds_read_b128 v[26:29], v156 offset:24864
	ds_read_b128 v[30:33], v156 offset:28960
	ds_read_b128 v[34:37], v156 offset:33056
	s_waitcnt vmcnt(59) lgkmcnt(9)
	v_fmac_f32_e32 v144, v184, v68
	v_fmac_f32_e32 v145, v188, v68
	v_fmac_f32_e32 v146, v192, v68
	v_fmac_f32_e32 v147, v196, v68
	v_fmac_f32_e32 v148, v200, v68
	v_fmac_f32_e32 v149, v204, v68
	v_fmac_f32_e32 v150, v208, v68
	v_fmac_f32_e32 v151, v212, v68
	v_fmac_f32_e32 v152, v216, v68
	s_waitcnt vmcnt(58)
	v_fmac_f32_e32 v144, v185, v69
	v_fmac_f32_e32 v145, v189, v69
	v_fmac_f32_e32 v146, v193, v69
	v_fmac_f32_e32 v147, v197, v69
	v_fmac_f32_e32 v148, v201, v69
	v_fmac_f32_e32 v149, v205, v69
	v_fmac_f32_e32 v150, v209, v69
	v_fmac_f32_e32 v151, v213, v69
	v_fmac_f32_e32 v152, v217, v69
	s_waitcnt vmcnt(57)
	v_fmac_f32_e32 v144, v186, v70
	v_fmac_f32_e32 v145, v190, v70
	v_fmac_f32_e32 v146, v194, v70
	v_fmac_f32_e32 v147, v198, v70
	v_fmac_f32_e32 v148, v202, v70
	v_fmac_f32_e32 v149, v206, v70
	v_fmac_f32_e32 v150, v210, v70
	v_fmac_f32_e32 v151, v214, v70
	v_fmac_f32_e32 v152, v218, v70
	s_waitcnt vmcnt(56)
	v_fmac_f32_e32 v144, v187, v71
	v_fmac_f32_e32 v145, v191, v71
	v_fmac_f32_e32 v146, v195, v71
	v_fmac_f32_e32 v147, v199, v71
	v_fmac_f32_e32 v148, v203, v71
	v_fmac_f32_e32 v149, v207, v71
	v_fmac_f32_e32 v150, v211, v71
	v_fmac_f32_e32 v151, v215, v71
	v_fmac_f32_e32 v152, v219, v71
	ds_read_b128 v[184:187], v156 offset:304
	ds_read_b128 v[188:191], v156 offset:4400
	ds_read_b128 v[192:195], v156 offset:8496
	ds_read_b128 v[196:199], v156 offset:12592
	ds_read_b128 v[200:203], v156 offset:16688
	ds_read_b128 v[204:207], v156 offset:20784
	ds_read_b128 v[208:211], v156 offset:24880
	ds_read_b128 v[212:215], v156 offset:28976
	ds_read_b128 v[216:219], v156 offset:33072
	s_waitcnt vmcnt(55) lgkmcnt(9)
	v_fmac_f32_e32 v144, v2, v72
	v_fmac_f32_e32 v145, v6, v72
	v_fmac_f32_e32 v146, v10, v72
	v_fmac_f32_e32 v147, v14, v72
	v_fmac_f32_e32 v148, v18, v72
	v_fmac_f32_e32 v149, v22, v72
	v_fmac_f32_e32 v150, v26, v72
	v_fmac_f32_e32 v151, v30, v72
	v_fmac_f32_e32 v152, v34, v72
	s_waitcnt vmcnt(54)
	v_fmac_f32_e32 v144, v3, v73
	v_fmac_f32_e32 v145, v7, v73
	v_fmac_f32_e32 v146, v11, v73
	v_fmac_f32_e32 v147, v15, v73
	v_fmac_f32_e32 v148, v19, v73
	v_fmac_f32_e32 v149, v23, v73
	v_fmac_f32_e32 v150, v27, v73
	v_fmac_f32_e32 v151, v31, v73
	v_fmac_f32_e32 v152, v35, v73
	s_waitcnt vmcnt(53)
	v_fmac_f32_e32 v144, v4, v74
	v_fmac_f32_e32 v145, v8, v74
	v_fmac_f32_e32 v146, v12, v74
	v_fmac_f32_e32 v147, v16, v74
	v_fmac_f32_e32 v148, v20, v74
	v_fmac_f32_e32 v149, v24, v74
	v_fmac_f32_e32 v150, v28, v74
	v_fmac_f32_e32 v151, v32, v74
	v_fmac_f32_e32 v152, v36, v74
	s_waitcnt vmcnt(52)
	v_fmac_f32_e32 v144, v5, v75
	v_fmac_f32_e32 v145, v9, v75
	v_fmac_f32_e32 v146, v13, v75
	v_fmac_f32_e32 v147, v17, v75
	v_fmac_f32_e32 v148, v21, v75
	v_fmac_f32_e32 v149, v25, v75
	v_fmac_f32_e32 v150, v29, v75
	v_fmac_f32_e32 v151, v33, v75
	v_fmac_f32_e32 v152, v37, v75
	ds_read_b128 v[2:5], v156 offset:320
	ds_read_b128 v[6:9], v156 offset:4416
	ds_read_b128 v[10:13], v156 offset:8512
	ds_read_b128 v[14:17], v156 offset:12608
	ds_read_b128 v[18:21], v156 offset:16704
	ds_read_b128 v[22:25], v156 offset:20800
	ds_read_b128 v[26:29], v156 offset:24896
	ds_read_b128 v[30:33], v156 offset:28992
	ds_read_b128 v[34:37], v156 offset:33088
	s_waitcnt vmcnt(51) lgkmcnt(9)
	v_fmac_f32_e32 v144, v184, v76
	v_fmac_f32_e32 v145, v188, v76
	v_fmac_f32_e32 v146, v192, v76
	v_fmac_f32_e32 v147, v196, v76
	v_fmac_f32_e32 v148, v200, v76
	v_fmac_f32_e32 v149, v204, v76
	v_fmac_f32_e32 v150, v208, v76
	v_fmac_f32_e32 v151, v212, v76
	v_fmac_f32_e32 v152, v216, v76
	s_waitcnt vmcnt(50)
	v_fmac_f32_e32 v144, v185, v77
	v_fmac_f32_e32 v145, v189, v77
	v_fmac_f32_e32 v146, v193, v77
	v_fmac_f32_e32 v147, v197, v77
	v_fmac_f32_e32 v148, v201, v77
	v_fmac_f32_e32 v149, v205, v77
	v_fmac_f32_e32 v150, v209, v77
	v_fmac_f32_e32 v151, v213, v77
	v_fmac_f32_e32 v152, v217, v77
	s_waitcnt vmcnt(49)
	v_fmac_f32_e32 v144, v186, v78
	v_fmac_f32_e32 v145, v190, v78
	v_fmac_f32_e32 v146, v194, v78
	v_fmac_f32_e32 v147, v198, v78
	v_fmac_f32_e32 v148, v202, v78
	v_fmac_f32_e32 v149, v206, v78
	v_fmac_f32_e32 v150, v210, v78
	v_fmac_f32_e32 v151, v214, v78
	v_fmac_f32_e32 v152, v218, v78
	s_waitcnt vmcnt(48)
	v_fmac_f32_e32 v144, v187, v79
	v_fmac_f32_e32 v145, v191, v79
	v_fmac_f32_e32 v146, v195, v79
	v_fmac_f32_e32 v147, v199, v79
	v_fmac_f32_e32 v148, v203, v79
	v_fmac_f32_e32 v149, v207, v79
	v_fmac_f32_e32 v150, v211, v79
	v_fmac_f32_e32 v151, v215, v79
	v_fmac_f32_e32 v152, v219, v79
	ds_read_b128 v[184:187], v156 offset:336
	ds_read_b128 v[188:191], v156 offset:4432
	ds_read_b128 v[192:195], v156 offset:8528
	ds_read_b128 v[196:199], v156 offset:12624
	ds_read_b128 v[200:203], v156 offset:16720
	ds_read_b128 v[204:207], v156 offset:20816
	ds_read_b128 v[208:211], v156 offset:24912
	ds_read_b128 v[212:215], v156 offset:29008
	ds_read_b128 v[216:219], v156 offset:33104
	s_waitcnt vmcnt(47) lgkmcnt(9)
	v_fmac_f32_e32 v144, v2, v80
	v_fmac_f32_e32 v145, v6, v80
	v_fmac_f32_e32 v146, v10, v80
	v_fmac_f32_e32 v147, v14, v80
	v_fmac_f32_e32 v148, v18, v80
	v_fmac_f32_e32 v149, v22, v80
	v_fmac_f32_e32 v150, v26, v80
	v_fmac_f32_e32 v151, v30, v80
	v_fmac_f32_e32 v152, v34, v80
	s_waitcnt vmcnt(46)
	v_fmac_f32_e32 v144, v3, v81
	v_fmac_f32_e32 v145, v7, v81
	v_fmac_f32_e32 v146, v11, v81
	v_fmac_f32_e32 v147, v15, v81
	v_fmac_f32_e32 v148, v19, v81
	v_fmac_f32_e32 v149, v23, v81
	v_fmac_f32_e32 v150, v27, v81
	v_fmac_f32_e32 v151, v31, v81
	v_fmac_f32_e32 v152, v35, v81
	s_waitcnt vmcnt(45)
	v_fmac_f32_e32 v144, v4, v83
	v_fmac_f32_e32 v145, v8, v83
	v_fmac_f32_e32 v146, v12, v83
	v_fmac_f32_e32 v147, v16, v83
	v_fmac_f32_e32 v148, v20, v83
	v_fmac_f32_e32 v149, v24, v83
	v_fmac_f32_e32 v150, v28, v83
	v_fmac_f32_e32 v151, v32, v83
	v_fmac_f32_e32 v152, v36, v83
	s_waitcnt vmcnt(44)
	v_fmac_f32_e32 v144, v5, v84
	v_fmac_f32_e32 v145, v9, v84
	v_fmac_f32_e32 v146, v13, v84
	v_fmac_f32_e32 v147, v17, v84
	v_fmac_f32_e32 v148, v21, v84
	v_fmac_f32_e32 v149, v25, v84
	v_fmac_f32_e32 v150, v29, v84
	v_fmac_f32_e32 v151, v33, v84
	v_fmac_f32_e32 v152, v37, v84
	ds_read_b128 v[2:5], v156 offset:352
	ds_read_b128 v[6:9], v156 offset:4448
	ds_read_b128 v[10:13], v156 offset:8544
	ds_read_b128 v[14:17], v156 offset:12640
	ds_read_b128 v[18:21], v156 offset:16736
	ds_read_b128 v[22:25], v156 offset:20832
	ds_read_b128 v[26:29], v156 offset:24928
	ds_read_b128 v[30:33], v156 offset:29024
	ds_read_b128 v[34:37], v156 offset:33120
	s_waitcnt vmcnt(43) lgkmcnt(9)
	v_fmac_f32_e32 v144, v184, v85
	v_fmac_f32_e32 v145, v188, v85
	v_fmac_f32_e32 v146, v192, v85
	v_fmac_f32_e32 v147, v196, v85
	v_fmac_f32_e32 v148, v200, v85
	v_fmac_f32_e32 v149, v204, v85
	v_fmac_f32_e32 v150, v208, v85
	v_fmac_f32_e32 v151, v212, v85
	v_fmac_f32_e32 v152, v216, v85
	s_waitcnt vmcnt(42)
	v_fmac_f32_e32 v144, v185, v86
	v_fmac_f32_e32 v145, v189, v86
	v_fmac_f32_e32 v146, v193, v86
	v_fmac_f32_e32 v147, v197, v86
	v_fmac_f32_e32 v148, v201, v86
	v_fmac_f32_e32 v149, v205, v86
	v_fmac_f32_e32 v150, v209, v86
	v_fmac_f32_e32 v151, v213, v86
	v_fmac_f32_e32 v152, v217, v86
	s_waitcnt vmcnt(41)
	v_fmac_f32_e32 v144, v186, v87
	v_fmac_f32_e32 v145, v190, v87
	v_fmac_f32_e32 v146, v194, v87
	v_fmac_f32_e32 v147, v198, v87
	v_fmac_f32_e32 v148, v202, v87
	v_fmac_f32_e32 v149, v206, v87
	v_fmac_f32_e32 v150, v210, v87
	v_fmac_f32_e32 v151, v214, v87
	v_fmac_f32_e32 v152, v218, v87
	s_waitcnt vmcnt(40)
	v_fmac_f32_e32 v144, v187, v88
	v_fmac_f32_e32 v145, v191, v88
	v_fmac_f32_e32 v146, v195, v88
	v_fmac_f32_e32 v147, v199, v88
	v_fmac_f32_e32 v148, v203, v88
	v_fmac_f32_e32 v149, v207, v88
	v_fmac_f32_e32 v150, v211, v88
	v_fmac_f32_e32 v151, v215, v88
	v_fmac_f32_e32 v152, v219, v88
	ds_read_b128 v[184:187], v156 offset:368
	ds_read_b128 v[188:191], v156 offset:4464
	ds_read_b128 v[192:195], v156 offset:8560
	ds_read_b128 v[196:199], v156 offset:12656
	ds_read_b128 v[200:203], v156 offset:16752
	ds_read_b128 v[204:207], v156 offset:20848
	ds_read_b128 v[208:211], v156 offset:24944
	ds_read_b128 v[212:215], v156 offset:29040
	ds_read_b128 v[216:219], v156 offset:33136
	s_waitcnt vmcnt(39) lgkmcnt(9)
	v_fmac_f32_e32 v144, v2, v89
	v_fmac_f32_e32 v145, v6, v89
	v_fmac_f32_e32 v146, v10, v89
	v_fmac_f32_e32 v147, v14, v89
	v_fmac_f32_e32 v148, v18, v89
	v_fmac_f32_e32 v149, v22, v89
	v_fmac_f32_e32 v150, v26, v89
	v_fmac_f32_e32 v151, v30, v89
	v_fmac_f32_e32 v152, v34, v89
	s_waitcnt vmcnt(38)
	v_fmac_f32_e32 v144, v3, v90
	v_fmac_f32_e32 v145, v7, v90
	v_fmac_f32_e32 v146, v11, v90
	v_fmac_f32_e32 v147, v15, v90
	v_fmac_f32_e32 v148, v19, v90
	v_fmac_f32_e32 v149, v23, v90
	v_fmac_f32_e32 v150, v27, v90
	v_fmac_f32_e32 v151, v31, v90
	v_fmac_f32_e32 v152, v35, v90
	s_waitcnt vmcnt(37)
	v_fmac_f32_e32 v144, v4, v91
	v_fmac_f32_e32 v145, v8, v91
	v_fmac_f32_e32 v146, v12, v91
	v_fmac_f32_e32 v147, v16, v91
	v_fmac_f32_e32 v148, v20, v91
	v_fmac_f32_e32 v149, v24, v91
	v_fmac_f32_e32 v150, v28, v91
	v_fmac_f32_e32 v151, v32, v91
	v_fmac_f32_e32 v152, v36, v91
	s_waitcnt vmcnt(36)
	v_fmac_f32_e32 v144, v5, v92
	v_fmac_f32_e32 v145, v9, v92
	v_fmac_f32_e32 v146, v13, v92
	v_fmac_f32_e32 v147, v17, v92
	v_fmac_f32_e32 v148, v21, v92
	v_fmac_f32_e32 v149, v25, v92
	v_fmac_f32_e32 v150, v29, v92
	v_fmac_f32_e32 v151, v33, v92
	v_fmac_f32_e32 v152, v37, v92
	ds_read_b128 v[2:5], v156 offset:384
	ds_read_b128 v[6:9], v156 offset:4480
	ds_read_b128 v[10:13], v156 offset:8576
	ds_read_b128 v[14:17], v156 offset:12672
	ds_read_b128 v[18:21], v156 offset:16768
	ds_read_b128 v[22:25], v156 offset:20864
	ds_read_b128 v[26:29], v156 offset:24960
	ds_read_b128 v[30:33], v156 offset:29056
	ds_read_b128 v[34:37], v156 offset:33152
	s_waitcnt vmcnt(35) lgkmcnt(9)
	v_fmac_f32_e32 v144, v184, v93
	v_fmac_f32_e32 v145, v188, v93
	v_fmac_f32_e32 v146, v192, v93
	v_fmac_f32_e32 v147, v196, v93
	v_fmac_f32_e32 v148, v200, v93
	v_fmac_f32_e32 v149, v204, v93
	v_fmac_f32_e32 v150, v208, v93
	v_fmac_f32_e32 v151, v212, v93
	v_fmac_f32_e32 v152, v216, v93
	s_waitcnt vmcnt(34)
	v_fmac_f32_e32 v144, v185, v94
	v_fmac_f32_e32 v145, v189, v94
	v_fmac_f32_e32 v146, v193, v94
	v_fmac_f32_e32 v147, v197, v94
	v_fmac_f32_e32 v148, v201, v94
	v_fmac_f32_e32 v149, v205, v94
	v_fmac_f32_e32 v150, v209, v94
	v_fmac_f32_e32 v151, v213, v94
	v_fmac_f32_e32 v152, v217, v94
	s_waitcnt vmcnt(33)
	v_fmac_f32_e32 v144, v186, v95
	v_fmac_f32_e32 v145, v190, v95
	v_fmac_f32_e32 v146, v194, v95
	v_fmac_f32_e32 v147, v198, v95
	v_fmac_f32_e32 v148, v202, v95
	v_fmac_f32_e32 v149, v206, v95
	v_fmac_f32_e32 v150, v210, v95
	v_fmac_f32_e32 v151, v214, v95
	v_fmac_f32_e32 v152, v218, v95
	s_waitcnt vmcnt(32)
	v_fmac_f32_e32 v144, v187, v96
	v_fmac_f32_e32 v145, v191, v96
	v_fmac_f32_e32 v146, v195, v96
	v_fmac_f32_e32 v147, v199, v96
	v_fmac_f32_e32 v148, v203, v96
	v_fmac_f32_e32 v149, v207, v96
	v_fmac_f32_e32 v150, v211, v96
	v_fmac_f32_e32 v151, v215, v96
	v_fmac_f32_e32 v152, v219, v96
	ds_read_b128 v[184:187], v156 offset:400
	ds_read_b128 v[188:191], v156 offset:4496
	ds_read_b128 v[192:195], v156 offset:8592
	ds_read_b128 v[196:199], v156 offset:12688
	ds_read_b128 v[200:203], v156 offset:16784
	ds_read_b128 v[204:207], v156 offset:20880
	ds_read_b128 v[208:211], v156 offset:24976
	ds_read_b128 v[212:215], v156 offset:29072
	ds_read_b128 v[216:219], v156 offset:33168
	s_waitcnt vmcnt(31) lgkmcnt(9)
	v_fmac_f32_e32 v144, v2, v97
	v_fmac_f32_e32 v145, v6, v97
	v_fmac_f32_e32 v146, v10, v97
	v_fmac_f32_e32 v147, v14, v97
	v_fmac_f32_e32 v148, v18, v97
	v_fmac_f32_e32 v149, v22, v97
	v_fmac_f32_e32 v150, v26, v97
	v_fmac_f32_e32 v151, v30, v97
	v_fmac_f32_e32 v152, v34, v97
	s_waitcnt vmcnt(30)
	v_fmac_f32_e32 v144, v3, v98
	v_fmac_f32_e32 v145, v7, v98
	v_fmac_f32_e32 v146, v11, v98
	v_fmac_f32_e32 v147, v15, v98
	v_fmac_f32_e32 v148, v19, v98
	v_fmac_f32_e32 v149, v23, v98
	v_fmac_f32_e32 v150, v27, v98
	v_fmac_f32_e32 v151, v31, v98
	v_fmac_f32_e32 v152, v35, v98
	s_waitcnt vmcnt(29)
	v_fmac_f32_e32 v144, v4, v99
	v_fmac_f32_e32 v145, v8, v99
	v_fmac_f32_e32 v146, v12, v99
	v_fmac_f32_e32 v147, v16, v99
	v_fmac_f32_e32 v148, v20, v99
	v_fmac_f32_e32 v149, v24, v99
	v_fmac_f32_e32 v150, v28, v99
	v_fmac_f32_e32 v151, v32, v99
	v_fmac_f32_e32 v152, v36, v99
	s_waitcnt vmcnt(28)
	v_fmac_f32_e32 v144, v5, v100
	v_fmac_f32_e32 v145, v9, v100
	v_fmac_f32_e32 v146, v13, v100
	v_fmac_f32_e32 v147, v17, v100
	v_fmac_f32_e32 v148, v21, v100
	v_fmac_f32_e32 v149, v25, v100
	v_fmac_f32_e32 v150, v29, v100
	v_fmac_f32_e32 v151, v33, v100
	v_fmac_f32_e32 v152, v37, v100
	ds_read_b128 v[2:5], v156 offset:416
	ds_read_b128 v[6:9], v156 offset:4512
	ds_read_b128 v[10:13], v156 offset:8608
	ds_read_b128 v[14:17], v156 offset:12704
	ds_read_b128 v[18:21], v156 offset:16800
	ds_read_b128 v[22:25], v156 offset:20896
	ds_read_b128 v[26:29], v156 offset:24992
	ds_read_b128 v[30:33], v156 offset:29088
	ds_read_b128 v[34:37], v156 offset:33184
	s_waitcnt vmcnt(27) lgkmcnt(9)
	v_fmac_f32_e32 v144, v184, v101
	v_fmac_f32_e32 v145, v188, v101
	v_fmac_f32_e32 v146, v192, v101
	v_fmac_f32_e32 v147, v196, v101
	v_fmac_f32_e32 v148, v200, v101
	v_fmac_f32_e32 v149, v204, v101
	v_fmac_f32_e32 v150, v208, v101
	v_fmac_f32_e32 v151, v212, v101
	v_fmac_f32_e32 v152, v216, v101
	s_waitcnt vmcnt(26)
	v_fmac_f32_e32 v144, v185, v102
	v_fmac_f32_e32 v145, v189, v102
	v_fmac_f32_e32 v146, v193, v102
	v_fmac_f32_e32 v147, v197, v102
	v_fmac_f32_e32 v148, v201, v102
	v_fmac_f32_e32 v149, v205, v102
	v_fmac_f32_e32 v150, v209, v102
	v_fmac_f32_e32 v151, v213, v102
	v_fmac_f32_e32 v152, v217, v102
	s_waitcnt vmcnt(25)
	v_fmac_f32_e32 v144, v186, v103
	v_fmac_f32_e32 v145, v190, v103
	v_fmac_f32_e32 v146, v194, v103
	v_fmac_f32_e32 v147, v198, v103
	v_fmac_f32_e32 v148, v202, v103
	v_fmac_f32_e32 v149, v206, v103
	v_fmac_f32_e32 v150, v210, v103
	v_fmac_f32_e32 v151, v214, v103
	v_fmac_f32_e32 v152, v218, v103
	s_waitcnt vmcnt(24)
	v_fmac_f32_e32 v144, v187, v104
	v_fmac_f32_e32 v145, v191, v104
	v_fmac_f32_e32 v146, v195, v104
	v_fmac_f32_e32 v147, v199, v104
	v_fmac_f32_e32 v148, v203, v104
	v_fmac_f32_e32 v149, v207, v104
	v_fmac_f32_e32 v150, v211, v104
	v_fmac_f32_e32 v151, v215, v104
	v_fmac_f32_e32 v152, v219, v104
	ds_read_b128 v[184:187], v156 offset:432
	ds_read_b128 v[188:191], v156 offset:4528
	ds_read_b128 v[192:195], v156 offset:8624
	ds_read_b128 v[196:199], v156 offset:12720
	ds_read_b128 v[200:203], v156 offset:16816
	ds_read_b128 v[204:207], v156 offset:20912
	ds_read_b128 v[208:211], v156 offset:25008
	ds_read_b128 v[212:215], v156 offset:29104
	ds_read_b128 v[216:219], v156 offset:33200
	s_waitcnt vmcnt(23) lgkmcnt(9)
	v_fmac_f32_e32 v144, v2, v105
	v_fmac_f32_e32 v145, v6, v105
	v_fmac_f32_e32 v146, v10, v105
	v_fmac_f32_e32 v147, v14, v105
	v_fmac_f32_e32 v148, v18, v105
	v_fmac_f32_e32 v149, v22, v105
	v_fmac_f32_e32 v150, v26, v105
	v_fmac_f32_e32 v151, v30, v105
	v_fmac_f32_e32 v152, v34, v105
	s_waitcnt vmcnt(22)
	v_fmac_f32_e32 v144, v3, v106
	v_fmac_f32_e32 v145, v7, v106
	v_fmac_f32_e32 v146, v11, v106
	v_fmac_f32_e32 v147, v15, v106
	v_fmac_f32_e32 v148, v19, v106
	v_fmac_f32_e32 v149, v23, v106
	v_fmac_f32_e32 v150, v27, v106
	v_fmac_f32_e32 v151, v31, v106
	v_fmac_f32_e32 v152, v35, v106
	s_waitcnt vmcnt(21)
	v_fmac_f32_e32 v144, v4, v107
	v_fmac_f32_e32 v145, v8, v107
	v_fmac_f32_e32 v146, v12, v107
	v_fmac_f32_e32 v147, v16, v107
	v_fmac_f32_e32 v148, v20, v107
	v_fmac_f32_e32 v149, v24, v107
	v_fmac_f32_e32 v150, v28, v107
	v_fmac_f32_e32 v151, v32, v107
	v_fmac_f32_e32 v152, v36, v107
	s_waitcnt vmcnt(20)
	v_fmac_f32_e32 v144, v5, v108
	v_fmac_f32_e32 v145, v9, v108
	v_fmac_f32_e32 v146, v13, v108
	v_fmac_f32_e32 v147, v17, v108
	v_fmac_f32_e32 v148, v21, v108
	v_fmac_f32_e32 v149, v25, v108
	v_fmac_f32_e32 v150, v29, v108
	v_fmac_f32_e32 v151, v33, v108
	v_fmac_f32_e32 v152, v37, v108
	ds_read_b128 v[2:5], v156 offset:448
	ds_read_b128 v[6:9], v156 offset:4544
	ds_read_b128 v[10:13], v156 offset:8640
	ds_read_b128 v[14:17], v156 offset:12736
	ds_read_b128 v[18:21], v156 offset:16832
	ds_read_b128 v[22:25], v156 offset:20928
	ds_read_b128 v[26:29], v156 offset:25024
	ds_read_b128 v[30:33], v156 offset:29120
	ds_read_b128 v[34:37], v156 offset:33216
	s_waitcnt vmcnt(19) lgkmcnt(9)
	v_fmac_f32_e32 v144, v184, v109
	v_fmac_f32_e32 v145, v188, v109
	v_fmac_f32_e32 v146, v192, v109
	v_fmac_f32_e32 v147, v196, v109
	v_fmac_f32_e32 v148, v200, v109
	v_fmac_f32_e32 v149, v204, v109
	v_fmac_f32_e32 v150, v208, v109
	v_fmac_f32_e32 v151, v212, v109
	v_fmac_f32_e32 v152, v216, v109
	s_waitcnt vmcnt(18)
	v_fmac_f32_e32 v144, v185, v110
	v_fmac_f32_e32 v145, v189, v110
	v_fmac_f32_e32 v146, v193, v110
	v_fmac_f32_e32 v147, v197, v110
	v_fmac_f32_e32 v148, v201, v110
	v_fmac_f32_e32 v149, v205, v110
	v_fmac_f32_e32 v150, v209, v110
	v_fmac_f32_e32 v151, v213, v110
	v_fmac_f32_e32 v152, v217, v110
	s_waitcnt vmcnt(17)
	v_fmac_f32_e32 v144, v186, v111
	v_fmac_f32_e32 v145, v190, v111
	v_fmac_f32_e32 v146, v194, v111
	v_fmac_f32_e32 v147, v198, v111
	v_fmac_f32_e32 v148, v202, v111
	v_fmac_f32_e32 v149, v206, v111
	v_fmac_f32_e32 v150, v210, v111
	v_fmac_f32_e32 v151, v214, v111
	v_fmac_f32_e32 v152, v218, v111
	s_waitcnt vmcnt(16)
	v_fmac_f32_e32 v144, v187, v112
	v_fmac_f32_e32 v145, v191, v112
	v_fmac_f32_e32 v146, v195, v112
	v_fmac_f32_e32 v147, v199, v112
	v_fmac_f32_e32 v148, v203, v112
	v_fmac_f32_e32 v149, v207, v112
	v_fmac_f32_e32 v150, v211, v112
	v_fmac_f32_e32 v151, v215, v112
	v_fmac_f32_e32 v152, v219, v112
	ds_read_b128 v[184:187], v156 offset:464
	ds_read_b128 v[188:191], v156 offset:4560
	ds_read_b128 v[192:195], v156 offset:8656
	ds_read_b128 v[196:199], v156 offset:12752
	ds_read_b128 v[200:203], v156 offset:16848
	ds_read_b128 v[204:207], v156 offset:20944
	ds_read_b128 v[208:211], v156 offset:25040
	ds_read_b128 v[212:215], v156 offset:29136
	ds_read_b128 v[216:219], v156 offset:33232
	s_waitcnt vmcnt(15) lgkmcnt(9)
	v_fmac_f32_e32 v144, v2, v113
	v_fmac_f32_e32 v145, v6, v113
	v_fmac_f32_e32 v146, v10, v113
	v_fmac_f32_e32 v147, v14, v113
	v_fmac_f32_e32 v148, v18, v113
	v_fmac_f32_e32 v149, v22, v113
	v_fmac_f32_e32 v150, v26, v113
	v_fmac_f32_e32 v151, v30, v113
	v_fmac_f32_e32 v152, v34, v113
	s_waitcnt vmcnt(14)
	v_fmac_f32_e32 v144, v3, v114
	v_fmac_f32_e32 v145, v7, v114
	v_fmac_f32_e32 v146, v11, v114
	v_fmac_f32_e32 v147, v15, v114
	v_fmac_f32_e32 v148, v19, v114
	v_fmac_f32_e32 v149, v23, v114
	v_fmac_f32_e32 v150, v27, v114
	v_fmac_f32_e32 v151, v31, v114
	v_fmac_f32_e32 v152, v35, v114
	s_waitcnt vmcnt(13)
	v_fmac_f32_e32 v144, v4, v115
	v_fmac_f32_e32 v145, v8, v115
	v_fmac_f32_e32 v146, v12, v115
	v_fmac_f32_e32 v147, v16, v115
	v_fmac_f32_e32 v148, v20, v115
	v_fmac_f32_e32 v149, v24, v115
	v_fmac_f32_e32 v150, v28, v115
	v_fmac_f32_e32 v151, v32, v115
	v_fmac_f32_e32 v152, v36, v115
	s_waitcnt vmcnt(12)
	v_fmac_f32_e32 v144, v5, v116
	v_fmac_f32_e32 v145, v9, v116
	v_fmac_f32_e32 v146, v13, v116
	v_fmac_f32_e32 v147, v17, v116
	v_fmac_f32_e32 v148, v21, v116
	v_fmac_f32_e32 v149, v25, v116
	v_fmac_f32_e32 v150, v29, v116
	v_fmac_f32_e32 v151, v33, v116
	v_fmac_f32_e32 v152, v37, v116
	ds_read_b128 v[2:5], v156 offset:480
	ds_read_b128 v[6:9], v156 offset:4576
	ds_read_b128 v[10:13], v156 offset:8672
	ds_read_b128 v[14:17], v156 offset:12768
	ds_read_b128 v[18:21], v156 offset:16864
	ds_read_b128 v[22:25], v156 offset:20960
	ds_read_b128 v[26:29], v156 offset:25056
	ds_read_b128 v[30:33], v156 offset:29152
	ds_read_b128 v[34:37], v156 offset:33248
	s_waitcnt vmcnt(11) lgkmcnt(9)
	v_fmac_f32_e32 v144, v184, v117
	v_fmac_f32_e32 v145, v188, v117
	v_fmac_f32_e32 v146, v192, v117
	v_fmac_f32_e32 v147, v196, v117
	v_fmac_f32_e32 v148, v200, v117
	v_fmac_f32_e32 v149, v204, v117
	v_fmac_f32_e32 v150, v208, v117
	v_fmac_f32_e32 v151, v212, v117
	v_fmac_f32_e32 v152, v216, v117
	s_waitcnt vmcnt(10)
	v_fmac_f32_e32 v144, v185, v118
	v_fmac_f32_e32 v145, v189, v118
	v_fmac_f32_e32 v146, v193, v118
	v_fmac_f32_e32 v147, v197, v118
	v_fmac_f32_e32 v148, v201, v118
	v_fmac_f32_e32 v149, v205, v118
	v_fmac_f32_e32 v150, v209, v118
	v_fmac_f32_e32 v151, v213, v118
	v_fmac_f32_e32 v152, v217, v118
	s_waitcnt vmcnt(9)
	v_fmac_f32_e32 v144, v186, v119
	v_fmac_f32_e32 v145, v190, v119
	v_fmac_f32_e32 v146, v194, v119
	v_fmac_f32_e32 v147, v198, v119
	v_fmac_f32_e32 v148, v202, v119
	v_fmac_f32_e32 v149, v206, v119
	v_fmac_f32_e32 v150, v210, v119
	v_fmac_f32_e32 v151, v214, v119
	v_fmac_f32_e32 v152, v218, v119
	s_waitcnt vmcnt(8)
	v_fmac_f32_e32 v144, v187, v120
	v_fmac_f32_e32 v145, v191, v120
	v_fmac_f32_e32 v146, v195, v120
	v_fmac_f32_e32 v147, v199, v120
	v_fmac_f32_e32 v148, v203, v120
	v_fmac_f32_e32 v149, v207, v120
	v_fmac_f32_e32 v150, v211, v120
	v_fmac_f32_e32 v151, v215, v120
	v_fmac_f32_e32 v152, v219, v120
	ds_read_b128 v[184:187], v156 offset:496
	ds_read_b128 v[188:191], v156 offset:4592
	ds_read_b128 v[192:195], v156 offset:8688
	ds_read_b128 v[196:199], v156 offset:12784
	ds_read_b128 v[200:203], v156 offset:16880
	ds_read_b128 v[204:207], v156 offset:20976
	ds_read_b128 v[208:211], v156 offset:25072
	ds_read_b128 v[212:215], v156 offset:29168
	ds_read_b128 v[216:219], v156 offset:33264
	s_waitcnt vmcnt(7) lgkmcnt(9)
	v_fmac_f32_e32 v144, v2, v60
	v_fmac_f32_e32 v145, v6, v60
	v_fmac_f32_e32 v146, v10, v60
	v_fmac_f32_e32 v147, v14, v60
	v_fmac_f32_e32 v148, v18, v60
	v_fmac_f32_e32 v149, v22, v60
	v_fmac_f32_e32 v150, v26, v60
	v_fmac_f32_e32 v151, v30, v60
	v_fmac_f32_e32 v152, v34, v60
	s_waitcnt vmcnt(6)
	v_fmac_f32_e32 v144, v3, v61
	v_fmac_f32_e32 v145, v7, v61
	v_fmac_f32_e32 v146, v11, v61
	v_fmac_f32_e32 v147, v15, v61
	v_fmac_f32_e32 v148, v19, v61
	v_fmac_f32_e32 v149, v23, v61
	v_fmac_f32_e32 v150, v27, v61
	v_fmac_f32_e32 v151, v31, v61
	v_fmac_f32_e32 v152, v35, v61
	s_waitcnt vmcnt(5)
	v_fmac_f32_e32 v144, v4, v62
	v_fmac_f32_e32 v145, v8, v62
	v_fmac_f32_e32 v146, v12, v62
	v_fmac_f32_e32 v147, v16, v62
	v_fmac_f32_e32 v148, v20, v62
	v_fmac_f32_e32 v149, v24, v62
	v_fmac_f32_e32 v150, v28, v62
	v_fmac_f32_e32 v151, v32, v62
	v_fmac_f32_e32 v152, v36, v62
	s_waitcnt vmcnt(4)
	v_fmac_f32_e32 v144, v5, v63
	v_fmac_f32_e32 v145, v9, v63
	v_fmac_f32_e32 v146, v13, v63
	v_fmac_f32_e32 v147, v17, v63
	v_fmac_f32_e32 v148, v21, v63
	v_fmac_f32_e32 v149, v25, v63
	v_fmac_f32_e32 v150, v29, v63
	v_fmac_f32_e32 v151, v33, v63
	v_fmac_f32_e32 v152, v37, v63
	s_waitcnt vmcnt(3) lgkmcnt(0)
	v_fmac_f32_e32 v144, v184, v64
	v_fmac_f32_e32 v145, v188, v64
	v_fmac_f32_e32 v146, v192, v64
	v_fmac_f32_e32 v147, v196, v64
	v_fmac_f32_e32 v148, v200, v64
	v_fmac_f32_e32 v149, v204, v64
	v_fmac_f32_e32 v150, v208, v64
	v_fmac_f32_e32 v151, v212, v64
	v_fmac_f32_e32 v152, v216, v64
	s_waitcnt vmcnt(2)
	v_fmac_f32_e32 v144, v185, v65
	v_fmac_f32_e32 v145, v189, v65
	v_fmac_f32_e32 v146, v193, v65
	v_fmac_f32_e32 v147, v197, v65
	v_fmac_f32_e32 v148, v201, v65
	v_fmac_f32_e32 v149, v205, v65
	v_fmac_f32_e32 v150, v209, v65
	v_fmac_f32_e32 v151, v213, v65
	v_fmac_f32_e32 v152, v217, v65
	s_waitcnt vmcnt(1)
	v_fmac_f32_e32 v144, v186, v66
	v_fmac_f32_e32 v145, v190, v66
	v_fmac_f32_e32 v146, v194, v66
	v_fmac_f32_e32 v147, v198, v66
	v_fmac_f32_e32 v148, v202, v66
	v_fmac_f32_e32 v149, v206, v66
	v_fmac_f32_e32 v150, v210, v66
	v_fmac_f32_e32 v151, v214, v66
	v_fmac_f32_e32 v152, v218, v66
	s_waitcnt vmcnt(0)
	v_fmac_f32_e32 v144, v187, v67
	v_fmac_f32_e32 v145, v191, v67
	v_fmac_f32_e32 v146, v195, v67
	v_fmac_f32_e32 v147, v199, v67
	v_fmac_f32_e32 v148, v203, v67
	v_fmac_f32_e32 v149, v207, v67
	v_fmac_f32_e32 v150, v211, v67
	v_fmac_f32_e32 v151, v215, v67
	v_fmac_f32_e32 v152, v219, v67
	s_mul_i32 s15, s14, 2304
	v_add_u32_e32 v157, s15, v154
	ds_write_b32 v157, v144 offset:36864
	ds_write_b32 v157, v145 offset:37120
	ds_write_b32 v157, v146 offset:37376
	ds_write_b32 v157, v147 offset:37632
	ds_write_b32 v157, v148 offset:37888
	ds_write_b32 v157, v149 offset:38144
	ds_write_b32 v157, v150 offset:38400
	ds_write_b32 v157, v151 offset:38656
	ds_write_b32 v157, v152 offset:38912
	s_waitcnt lgkmcnt(0)
	s_barrier
	s_mul_i32 s15, s12, 12288
	s_lshl_b32 s16, s13, 2
	s_add_u32 s15, s15, s16
	s_add_u32 s8, s8, s15
	s_addc_u32 s9, s9, 0
	global_load_dword v155, v154, s[8:9]
	s_mul_i32 s15, s12, 110592
	s_add_u32 s15, s15, s16
	s_add_u32 s15, s15, 0x1040000
	s_add_u32 s10, s50, s15
	s_addc_u32 s11, s51, 0
	s_mul_i32 s16, s14, 256
	v_add_u32_e32 v157, s16, v154
	ds_read_b32 v160, v157 offset:36864
	ds_read_b32 v161, v157 offset:39168
	ds_read_b32 v162, v157 offset:41472
	ds_read_b32 v163, v157 offset:43776
	ds_read_b32 v164, v157 offset:46080
	ds_read_b32 v165, v157 offset:48384
	ds_read_b32 v166, v157 offset:50688
	ds_read_b32 v167, v157 offset:52992
	s_waitcnt vmcnt(0) lgkmcnt(0)
	v_add_f32_e32 v156, v155, v160
	v_add_f32_e32 v156, v156, v161
	v_add_f32_e32 v156, v156, v162
	v_add_f32_e32 v156, v156, v163
	v_add_f32_e32 v156, v156, v164
	v_add_f32_e32 v156, v156, v165
	v_add_f32_e32 v156, v156, v166
	v_add_f32_e32 v156, v156, v167
	s_mul_i32 s16, s14, 12288
	s_add_u32 s24, s10, s16
	s_addc_u32 s25, s11, 0
	global_store_dword v154, v156, s[24:25]
	s_cmp_eq_u32 s14, 0
	s_cbranch_scc0 .Lmd_done
	s_movk_i32 s16, 2048
	v_add_u32_e32 v157, s16, v154
	ds_read_b32 v160, v157 offset:36864
	ds_read_b32 v161, v157 offset:39168
	ds_read_b32 v162, v157 offset:41472
	ds_read_b32 v163, v157 offset:43776
	ds_read_b32 v164, v157 offset:46080
	ds_read_b32 v165, v157 offset:48384
	ds_read_b32 v166, v157 offset:50688
	ds_read_b32 v167, v157 offset:52992
	s_waitcnt vmcnt(0) lgkmcnt(0)
	v_add_f32_e32 v156, v155, v160
	v_add_f32_e32 v156, v156, v161
	v_add_f32_e32 v156, v156, v162
	v_add_f32_e32 v156, v156, v163
	v_add_f32_e32 v156, v156, v164
	v_add_f32_e32 v156, v156, v165
	v_add_f32_e32 v156, v156, v166
	v_add_f32_e32 v156, v156, v167
	s_mov_b32 s16, 98304
	s_add_u32 s24, s10, s16
	s_addc_u32 s25, s11, 0
	global_store_dword v154, v156, s[24:25]
.Lmd_done:
	s_waitcnt vmcnt(0)
	s_barrier
	s_branch .LBB0_14
